# GEMM phases: removed the redundant s_setprio 0/1 flip pair between the two MFMA blocks of each super-phase
# baseline (speedup 1.0000x reference)
; #define PG8_STAGE(bufoff, gbase, voff) do { _Pragma("unroll") for (int _i = 0; _i < 2; ++_i) \
;         __builtin_amdgcn_global_load_lds((const unsigned*)((const char*)(gbase) + (voff)[_i]), (PG8_LAS unsigned*)(lds + (bufoff) + ldsw + _i * 8192), 16, 0, 0); } while (0)
; #define PG8_LDA(dst, b, h) do { _Pragma("unroll") for (int m = 0; m < 4; ++m) _Pragma("unroll") for (int k = 0; k < 2; ++k) dst[m][k] = *(const PG8_LAS bf16x8*)(lds + PG8_SA(b, h) + aoff + m * 2048 + k * 1024); } while (0)
; #define PG8_LDB(dst, b, h) do { _Pragma("unroll") for (int n = 0; n < 2; ++n) _Pragma("unroll") for (int k = 0; k < 2; ++k) dst[n][k] = *(const PG8_LAS bf16x8*)(lds + PG8_SB(b, h) + boff + n * 2048 + k * 1024); } while (0)
; #define PG8_MMA(ai, bj, At, Bt) do { __builtin_amdgcn_s_setprio(1); _Pragma("unroll") for (int m = 0; m < 4; ++m) _Pragma("unroll") for (int n = 0; n < 2; ++n) _Pragma("unroll") for (int k = 0; k < 2; ++k) \
;         acc[ai][bj][m][n] = __builtin_amdgcn_mfma_f32_16x16x32_bf16(Bt[n][k], At[m][k], acc[ai][bj][m][n], 0, 0, 0); __builtin_amdgcn_s_setprio(0); } while (0)
; #define PG8_WAIT_V(n) asm volatile("s_waitcnt vmcnt(" #n ")" ::: "memory")
; #define PG8_WAIT_L(n) asm volatile("s_waitcnt lgkmcnt(" #n ")" ::: "memory")
; #define PG8_BAR __builtin_amdgcn_s_barrier()
; #define PG8_SCHED __builtin_amdgcn_sched_barrier(0)
; template <class Epi, class Sched, bool ALIGN_EPI = false, bool SP2 = false, bool MID = false>
; __device__ __forceinline__ void gemm_phase(PG8_LAS unsigned char* lds, const Gemm g, const Sched& S, const Epi& E) {
;     ...
;             PG8_LDB(B0, 0, 0); PG8_LDB(B1, 0, 1); PG8_SCHED; PG8_LDA(At, 0, 0); PG8_STAGE(PG8_SA(1, 1), a1 + hstep, voffA);
;             PG8_WAIT_V(8); PG8_WAIT_L(0); PG8_BAR; PG8_MMA(0, 0, At, B0); PG8_MMA(0, 1, At, B1); PG8_BAR; PG8_SCHED;
;             PG8_LDA(At, 0, 1); PG8_STAGE(PG8_SB(0, 0), b2, voffB); PG8_STAGE(PG8_SB(0, 1), b2 + hstep, voffB); PG8_STAGE(PG8_SA(0, 0), a2, voffA);
;             PG8_WAIT_V(8); PG8_WAIT_L(0); PG8_BAR; PG8_MMA(1, 0, At, B0); PG8_MMA(1, 1, At, B1); PG8_BAR; PG8_SCHED;
.LBB0_206:
	ds_read_b128 v[130:133], v176
	ds_read_b128 v[134:137], v176 offset:1024
	ds_read_b128 v[138:141], v176 offset:2048
	ds_read_b128 v[164:167], v176 offset:3072
	ds_read_b128 v[168:171], v177
	ds_read_b128 v[180:183], v177 offset:1024
	ds_read_b128 v[184:187], v177 offset:2048
	ds_read_b128 v[188:191], v177 offset:3072
	s_add_u32 s52, s4, 0xfff80080
	s_addc_u32 s53, s5, -1
	s_cmp_eq_u32 s51, 28
	s_cselect_b32 s75, s14, s53
	s_cselect_b32 s74, s15, s52
	s_cselect_b32 s73, s24, s27
	s_cselect_b32 s72, s25, s26
	v_lshl_add_u64 v[142:143], s[4:5], 0, v[156:157]
	s_add_i32 m0, s71, 0xc000
	ds_read_b128 v[192:195], v178
	ds_read_b128 v[200:203], v178 offset:1024
	ds_read_b128 v[204:207], v178 offset:2048
	ds_read_b128 v[208:211], v178 offset:3072
	ds_read_b128 v[212:215], v178 offset:4096
	ds_read_b128 v[216:219], v178 offset:5120
	ds_read_b128 v[220:223], v178 offset:6144
	ds_read_b128 v[224:227], v178 offset:7168
	global_load_lds_dwordx4 v[142:143], off
	v_lshl_add_u64 v[142:143], s[4:5], 0, v[158:159]
	s_add_i32 m0, s71, 0xe000
	s_nop 0
	global_load_lds_dwordx4 v[142:143], off
	s_waitcnt vmcnt(8)
	s_waitcnt lgkmcnt(0)
	s_barrier
	s_setprio 1
	s_waitcnt lgkmcnt(0)
	v_mfma_f32_16x16x32_bf16 v[126:129], v[130:133], v[192:195], v[126:129]
	v_mfma_f32_16x16x32_bf16 v[122:125], v[138:141], v[192:195], v[122:125]
	v_mfma_f32_16x16x32_bf16 v[110:113], v[130:133], v[204:207], v[110:113]
	v_mfma_f32_16x16x32_bf16 v[106:109], v[138:141], v[204:207], v[106:109]
	v_mfma_f32_16x16x32_bf16 v[94:97], v[130:133], v[212:215], v[94:97]
	v_mfma_f32_16x16x32_bf16 v[90:93], v[138:141], v[212:215], v[90:93]
	v_mfma_f32_16x16x32_bf16 v[78:81], v[130:133], v[220:223], v[78:81]
	v_mfma_f32_16x16x32_bf16 v[74:77], v[138:141], v[220:223], v[74:77]
	v_mfma_f32_16x16x32_bf16 v[126:129], v[134:137], v[200:203], v[126:129]
	v_mfma_f32_16x16x32_bf16 v[122:125], v[164:167], v[200:203], v[122:125]
	v_mfma_f32_16x16x32_bf16 v[110:113], v[134:137], v[208:211], v[110:113]
	v_mfma_f32_16x16x32_bf16 v[106:109], v[164:167], v[208:211], v[106:109]
	v_mfma_f32_16x16x32_bf16 v[94:97], v[134:137], v[216:219], v[94:97]
	v_mfma_f32_16x16x32_bf16 v[90:93], v[164:167], v[216:219], v[90:93]
	v_mfma_f32_16x16x32_bf16 v[78:81], v[134:137], v[224:227], v[78:81]
	v_mfma_f32_16x16x32_bf16 v[74:77], v[164:167], v[224:227], v[74:77]
	v_mfma_f32_16x16x32_bf16 v[118:121], v[168:171], v[192:195], v[118:121]
	v_mfma_f32_16x16x32_bf16 v[114:117], v[184:187], v[192:195], v[114:117]
	v_mfma_f32_16x16x32_bf16 v[102:105], v[168:171], v[204:207], v[102:105]
	v_mfma_f32_16x16x32_bf16 v[98:101], v[184:187], v[204:207], v[98:101]
	v_mfma_f32_16x16x32_bf16 v[86:89], v[168:171], v[212:215], v[86:89]
	v_mfma_f32_16x16x32_bf16 v[82:85], v[184:187], v[212:215], v[82:85]
	v_mfma_f32_16x16x32_bf16 v[70:73], v[168:171], v[220:223], v[70:73]
	v_mfma_f32_16x16x32_bf16 v[66:69], v[184:187], v[220:223], v[66:69]
	v_mfma_f32_16x16x32_bf16 v[118:121], v[180:183], v[200:203], v[118:121]
	v_mfma_f32_16x16x32_bf16 v[114:117], v[188:191], v[200:203], v[114:117]
	v_mfma_f32_16x16x32_bf16 v[102:105], v[180:183], v[208:211], v[102:105]
	v_mfma_f32_16x16x32_bf16 v[98:101], v[188:191], v[208:211], v[98:101]
	v_mfma_f32_16x16x32_bf16 v[86:89], v[180:183], v[216:219], v[86:89]
	v_mfma_f32_16x16x32_bf16 v[82:85], v[188:191], v[216:219], v[82:85]
	v_mfma_f32_16x16x32_bf16 v[70:73], v[180:183], v[224:227], v[70:73]
	v_mfma_f32_16x16x32_bf16 v[66:69], v[188:191], v[224:227], v[66:69]
	s_setprio 0
	s_barrier
	s_add_i32 s52, s62, s87
	v_lshl_add_u64 v[142:143], s[72:73], 0, v[144:145]
	s_mov_b32 m0, s52
	ds_read_b128 v[192:195], v178 offset:16384
	ds_read_b128 v[200:203], v178 offset:17408
	ds_read_b128 v[204:207], v178 offset:18432
	ds_read_b128 v[208:211], v178 offset:19456
	ds_read_b128 v[212:215], v178 offset:20480
	ds_read_b128 v[216:219], v178 offset:21504
	ds_read_b128 v[220:223], v178 offset:22528
	ds_read_b128 v[224:227], v178 offset:23552
	global_load_lds_dwordx4 v[142:143], off
	s_add_i32 m0, s52, 0x2000
	s_add_u32 s52, s72, 0x80000
	v_lshl_add_u64 v[172:173], s[72:73], 0, v[146:147]
	s_addc_u32 s53, s73, 0
	s_add_i32 s55, s12, s87
	global_load_lds_dwordx4 v[172:173], off
	v_lshl_add_u64 v[196:197], s[52:53], 0, v[144:145]
	s_mov_b32 m0, s55
	v_lshl_add_u64 v[228:229], s[74:75], 0, v[146:147]
	global_load_lds_dwordx4 v[196:197], off
	v_lshl_add_u64 v[196:197], s[52:53], 0, v[146:147]
	s_add_i32 m0, s55, 0x2000
	s_nop 0
	global_load_lds_dwordx4 v[196:197], off
	v_lshl_add_u64 v[196:197], s[74:75], 0, v[144:145]
	s_mov_b32 m0, s71
	s_nop 0
	global_load_lds_dwordx4 v[196:197], off
	s_mov_b32 m0, s88
	s_nop 0
	global_load_lds_dwordx4 v[228:229], off
	s_waitcnt vmcnt(8)
	s_waitcnt lgkmcnt(0)
	s_barrier
; #define PG8_STAGE(bufoff, gbase, voff) do { _Pragma("unroll") for (int _i = 0; _i < 2; ++_i) \
;         __builtin_amdgcn_global_load_lds((const unsigned*)((const char*)(gbase) + (voff)[_i]), (PG8_LAS unsigned*)(lds + (bufoff) + ldsw + _i * 8192), 16, 0, 0); } while (0)
; #define PG8_LDA(dst, b, h) do { _Pragma("unroll") for (int m = 0; m < 4; ++m) _Pragma("unroll") for (int k = 0; k < 2; ++k) dst[m][k] = *(const PG8_LAS bf16x8*)(lds + PG8_SA(b, h) + aoff + m * 2048 + k * 1024); } while (0)
; #define PG8_LDB(dst, b, h) do { _Pragma("unroll") for (int n = 0; n < 2; ++n) _Pragma("unroll") for (int k = 0; k < 2; ++k) dst[n][k] = *(const PG8_LAS bf16x8*)(lds + PG8_SB(b, h) + boff + n * 2048 + k * 1024); } while (0)
; #define PG8_MMA(ai, bj, At, Bt) do { __builtin_amdgcn_s_setprio(1); _Pragma("unroll") for (int m = 0; m < 4; ++m) _Pragma("unroll") for (int n = 0; n < 2; ++n) _Pragma("unroll") for (int k = 0; k < 2; ++k) \
;         acc[ai][bj][m][n] = __builtin_amdgcn_mfma_f32_16x16x32_bf16(Bt[n][k], At[m][k], acc[ai][bj][m][n], 0, 0, 0); __builtin_amdgcn_s_setprio(0); } while (0)
; #define PG8_WAIT_V(n) asm volatile("s_waitcnt vmcnt(" #n ")" ::: "memory")
; #define PG8_WAIT_L(n) asm volatile("s_waitcnt lgkmcnt(" #n ")" ::: "memory")
; #define PG8_BAR __builtin_amdgcn_s_barrier()
; #define PG8_SCHED __builtin_amdgcn_sched_barrier(0)
; template <class Epi, class Sched, bool ALIGN_EPI = false, bool SP2 = false, bool MID = false>
; __device__ __forceinline__ void gemm_phase(PG8_LAS unsigned char* lds, const Gemm g, const Sched& S, const Epi& E) {
;     ...
;             PG8_WAIT_V(8); PG8_WAIT_L(0); PG8_BAR; PG8_MMA(1, 0, At, B0); PG8_MMA(1, 1, At, B1); PG8_BAR; PG8_SCHED;
;             PG8_LDB(B0, 1, 0); PG8_LDB(B1, 1, 1); PG8_SCHED; PG8_LDA(At, 1, 0); PG8_STAGE(PG8_SA(0, 1), a2 + hstep, voffA);
;             PG8_WAIT_V(8); PG8_WAIT_L(0); PG8_BAR; PG8_MMA(0, 0, At, B0); PG8_MMA(0, 1, At, B1); PG8_BAR; PG8_SCHED;
	s_setprio 1
	s_waitcnt lgkmcnt(0)
	v_mfma_f32_16x16x32_bf16 v[62:65], v[130:133], v[192:195], v[62:65]
	v_mfma_f32_16x16x32_bf16 v[58:61], v[138:141], v[192:195], v[58:61]
	v_mfma_f32_16x16x32_bf16 v[46:49], v[130:133], v[204:207], v[46:49]
	v_mfma_f32_16x16x32_bf16 v[42:45], v[138:141], v[204:207], v[42:45]
	v_mfma_f32_16x16x32_bf16 v[30:33], v[130:133], v[212:215], v[30:33]
	v_mfma_f32_16x16x32_bf16 v[26:29], v[138:141], v[212:215], v[26:29]
	v_mfma_f32_16x16x32_bf16 v[14:17], v[130:133], v[220:223], v[14:17]
	v_mfma_f32_16x16x32_bf16 v[10:13], v[138:141], v[220:223], v[10:13]
	v_mfma_f32_16x16x32_bf16 v[62:65], v[134:137], v[200:203], v[62:65]
	v_mfma_f32_16x16x32_bf16 v[58:61], v[164:167], v[200:203], v[58:61]
	v_mfma_f32_16x16x32_bf16 v[46:49], v[134:137], v[208:211], v[46:49]
	v_mfma_f32_16x16x32_bf16 v[42:45], v[164:167], v[208:211], v[42:45]
	v_mfma_f32_16x16x32_bf16 v[30:33], v[134:137], v[216:219], v[30:33]
	v_mfma_f32_16x16x32_bf16 v[26:29], v[164:167], v[216:219], v[26:29]
	v_mfma_f32_16x16x32_bf16 v[14:17], v[134:137], v[224:227], v[14:17]
	v_mfma_f32_16x16x32_bf16 v[10:13], v[164:167], v[224:227], v[10:13]
	v_mfma_f32_16x16x32_bf16 v[54:57], v[168:171], v[192:195], v[54:57]
	v_mfma_f32_16x16x32_bf16 v[50:53], v[184:187], v[192:195], v[50:53]
	v_mfma_f32_16x16x32_bf16 v[38:41], v[168:171], v[204:207], v[38:41]
	v_mfma_f32_16x16x32_bf16 v[34:37], v[184:187], v[204:207], v[34:37]
	v_mfma_f32_16x16x32_bf16 v[22:25], v[168:171], v[212:215], v[22:25]
	v_mfma_f32_16x16x32_bf16 v[18:21], v[184:187], v[212:215], v[18:21]
	v_mfma_f32_16x16x32_bf16 v[6:9], v[168:171], v[220:223], v[6:9]
	v_mfma_f32_16x16x32_bf16 v[2:5], v[184:187], v[220:223], v[2:5]
	v_mfma_f32_16x16x32_bf16 v[54:57], v[180:183], v[200:203], v[54:57]
	v_mfma_f32_16x16x32_bf16 v[50:53], v[188:191], v[200:203], v[50:53]
	v_mfma_f32_16x16x32_bf16 v[38:41], v[180:183], v[208:211], v[38:41]
	v_mfma_f32_16x16x32_bf16 v[34:37], v[188:191], v[208:211], v[34:37]
	v_mfma_f32_16x16x32_bf16 v[22:25], v[180:183], v[216:219], v[22:25]
	v_mfma_f32_16x16x32_bf16 v[18:21], v[188:191], v[216:219], v[18:21]
	v_mfma_f32_16x16x32_bf16 v[6:9], v[180:183], v[224:227], v[6:9]
	v_mfma_f32_16x16x32_bf16 v[2:5], v[188:191], v[224:227], v[2:5]
	s_setprio 0
	s_barrier
	s_add_i32 s55, 0, 0x18000
	v_add_u32_e32 v148, s55, v174
	s_add_i32 s76, 0, 0x1c000
	ds_read_b128 v[130:133], v148
	ds_read_b128 v[134:137], v148 offset:1024
	ds_read_b128 v[138:141], v148 offset:2048
	ds_read_b128 v[164:167], v148 offset:3072
	v_add_u32_e32 v148, s76, v174
	ds_read_b128 v[168:171], v148
	ds_read_b128 v[180:183], v148 offset:1024
	ds_read_b128 v[184:187], v148 offset:2048
	ds_read_b128 v[188:191], v148 offset:3072
	s_add_u32 s52, s74, 0x80000
	s_addc_u32 s53, s75, 0
	s_mov_b32 m0, s89
	v_lshl_add_u64 v[230:231], s[52:53], 0, v[144:145]
	ds_read_b128 v[192:195], v178 offset:32768
	ds_read_b128 v[200:203], v178 offset:33792
	ds_read_b128 v[204:207], v178 offset:34816
	ds_read_b128 v[208:211], v178 offset:35840
	ds_read_b128 v[212:215], v178 offset:36864
	ds_read_b128 v[216:219], v178 offset:37888
	ds_read_b128 v[220:223], v178 offset:38912
	ds_read_b128 v[224:227], v178 offset:39936
	global_load_lds_dwordx4 v[230:231], off
	v_lshl_add_u64 v[230:231], s[52:53], 0, v[146:147]
	s_mov_b32 m0, s90
	s_nop 0
	global_load_lds_dwordx4 v[230:231], off
	s_waitcnt vmcnt(8)
	s_waitcnt lgkmcnt(0)
	s_barrier
	s_setprio 1
	s_waitcnt lgkmcnt(0)
	v_mfma_f32_16x16x32_bf16 v[126:129], v[130:133], v[192:195], v[126:129]
	v_mfma_f32_16x16x32_bf16 v[122:125], v[138:141], v[192:195], v[122:125]
	v_mfma_f32_16x16x32_bf16 v[110:113], v[130:133], v[204:207], v[110:113]
	v_mfma_f32_16x16x32_bf16 v[106:109], v[138:141], v[204:207], v[106:109]
	v_mfma_f32_16x16x32_bf16 v[94:97], v[130:133], v[212:215], v[94:97]
	v_mfma_f32_16x16x32_bf16 v[90:93], v[138:141], v[212:215], v[90:93]
	v_mfma_f32_16x16x32_bf16 v[78:81], v[130:133], v[220:223], v[78:81]
	v_mfma_f32_16x16x32_bf16 v[74:77], v[138:141], v[220:223], v[74:77]
	v_mfma_f32_16x16x32_bf16 v[126:129], v[134:137], v[200:203], v[126:129]
	v_mfma_f32_16x16x32_bf16 v[122:125], v[164:167], v[200:203], v[122:125]
	v_mfma_f32_16x16x32_bf16 v[110:113], v[134:137], v[208:211], v[110:113]
	v_mfma_f32_16x16x32_bf16 v[106:109], v[164:167], v[208:211], v[106:109]
	v_mfma_f32_16x16x32_bf16 v[94:97], v[134:137], v[216:219], v[94:97]
	v_mfma_f32_16x16x32_bf16 v[90:93], v[164:167], v[216:219], v[90:93]
	v_mfma_f32_16x16x32_bf16 v[78:81], v[134:137], v[224:227], v[78:81]
	v_mfma_f32_16x16x32_bf16 v[74:77], v[164:167], v[224:227], v[74:77]
	v_mfma_f32_16x16x32_bf16 v[118:121], v[168:171], v[192:195], v[118:121]
	v_mfma_f32_16x16x32_bf16 v[114:117], v[184:187], v[192:195], v[114:117]
	v_mfma_f32_16x16x32_bf16 v[102:105], v[168:171], v[204:207], v[102:105]
	v_mfma_f32_16x16x32_bf16 v[98:101], v[184:187], v[204:207], v[98:101]
	v_mfma_f32_16x16x32_bf16 v[86:89], v[168:171], v[212:215], v[86:89]
	v_mfma_f32_16x16x32_bf16 v[82:85], v[184:187], v[212:215], v[82:85]
	v_mfma_f32_16x16x32_bf16 v[70:73], v[168:171], v[220:223], v[70:73]
	v_mfma_f32_16x16x32_bf16 v[66:69], v[184:187], v[220:223], v[66:69]
	v_mfma_f32_16x16x32_bf16 v[118:121], v[180:183], v[200:203], v[118:121]
	v_mfma_f32_16x16x32_bf16 v[114:117], v[188:191], v[200:203], v[114:117]
	v_mfma_f32_16x16x32_bf16 v[102:105], v[180:183], v[208:211], v[102:105]
	v_mfma_f32_16x16x32_bf16 v[98:101], v[188:191], v[208:211], v[98:101]
	v_mfma_f32_16x16x32_bf16 v[86:89], v[180:183], v[216:219], v[86:89]
	v_mfma_f32_16x16x32_bf16 v[82:85], v[188:191], v[216:219], v[82:85]
	v_mfma_f32_16x16x32_bf16 v[70:73], v[180:183], v[224:227], v[70:73]
	v_mfma_f32_16x16x32_bf16 v[66:69], v[188:191], v[224:227], v[66:69]
	s_setprio 0
	s_barrier
; #define PG8_STAGE(bufoff, gbase, voff) do { _Pragma("unroll") for (int _i = 0; _i < 2; ++_i) \
;         __builtin_amdgcn_global_load_lds((const unsigned*)((const char*)(gbase) + (voff)[_i]), (PG8_LAS unsigned*)(lds + (bufoff) + ldsw + _i * 8192), 16, 0, 0); } while (0)
; #define PG8_LDA(dst, b, h) do { _Pragma("unroll") for (int m = 0; m < 4; ++m) _Pragma("unroll") for (int k = 0; k < 2; ++k) dst[m][k] = *(const PG8_LAS bf16x8*)(lds + PG8_SA(b, h) + aoff + m * 2048 + k * 1024); } while (0)
; #define PG8_MMA(ai, bj, At, Bt) do { __builtin_amdgcn_s_setprio(1); _Pragma("unroll") for (int m = 0; m < 4; ++m) _Pragma("unroll") for (int n = 0; n < 2; ++n) _Pragma("unroll") for (int k = 0; k < 2; ++k) \
;         acc[ai][bj][m][n] = __builtin_amdgcn_mfma_f32_16x16x32_bf16(Bt[n][k], At[m][k], acc[ai][bj][m][n], 0, 0, 0); __builtin_amdgcn_s_setprio(0); } while (0)
; #define PG8_WAIT_V(n) asm volatile("s_waitcnt vmcnt(" #n ")" ::: "memory")
; #define PG8_WAIT_L(n) asm volatile("s_waitcnt lgkmcnt(" #n ")" ::: "memory")
; #define PG8_BAR __builtin_amdgcn_s_barrier()
; #define PG8_SCHED __builtin_amdgcn_sched_barrier(0)
; template <class Epi, class Sched, bool ALIGN_EPI = false, bool SP2 = false, bool MID = false>
; __device__ __forceinline__ void gemm_phase(PG8_LAS unsigned char* lds, const Gemm g, const Sched& S, const Epi& E) {
;     ...
;         for (int t = 0; t < nt; t += 2) {
;             const bool last = (t == nt - 2);
;             if constexpr (MID) { if (t == Epi::MID_T) { PG8_SCHED; E.mid(acc, cur, wr, wc, fr, fq); PG8_SCHED; } }
;             const char* a1 = cA + (size_t)(t + 1) * kstep;
;             const char* a2 = last ? nA : cA + (size_t)(t + 2) * kstep; const char* b2 = last ? nB : cB + (size_t)(t + 2) * kstep;
;             const char* a3 = a2 + kstep; const char* b3 = b2 + kstep;
;             if (last && has_next) S.a_ready(nxt);
;     ...
;             PG8_LDA(At, 1, 1); PG8_STAGE(PG8_SB(1, 0), b3, voffB); PG8_STAGE(PG8_SB(1, 1), b3 + hstep, voffB); PG8_STAGE(PG8_SA(1, 0), a3, voffA);
;             PG8_WAIT_V(8); PG8_WAIT_L(0); PG8_BAR; PG8_MMA(1, 0, At, B0); PG8_MMA(1, 1, At, B1); PG8_BAR; PG8_SCHED;
	s_add_i32 s52, s55, s87
	v_lshl_add_u64 v[142:143], v[142:143], 0, s[22:23]
	s_mov_b32 m0, s52
	ds_read_b128 v[192:195], v178 offset:49152
	ds_read_b128 v[200:203], v178 offset:50176
	ds_read_b128 v[204:207], v178 offset:51200
	ds_read_b128 v[208:211], v178 offset:52224
	ds_read_b128 v[212:215], v178 offset:53248
	ds_read_b128 v[216:219], v178 offset:54272
	ds_read_b128 v[220:223], v178 offset:55296
	ds_read_b128 v[224:227], v178 offset:56320
	global_load_lds_dwordx4 v[142:143], off
	s_add_i32 m0, s52, 0x2000
	s_add_u32 s52, s72, 0x80080
	v_lshl_add_u64 v[142:143], v[172:173], 0, s[22:23]
	s_addc_u32 s53, s73, 0
	s_add_i32 s55, s76, s87
	global_load_lds_dwordx4 v[142:143], off
	v_lshl_add_u64 v[142:143], s[52:53], 0, v[144:145]
	s_mov_b32 m0, s55
	s_nop 0
	global_load_lds_dwordx4 v[142:143], off
	v_lshl_add_u64 v[142:143], s[52:53], 0, v[146:147]
	s_add_i32 m0, s55, 0x2000
	s_nop 0
	global_load_lds_dwordx4 v[142:143], off
	v_lshl_add_u64 v[142:143], v[196:197], 0, s[22:23]
	s_mov_b32 m0, s94
	s_nop 0
	global_load_lds_dwordx4 v[142:143], off
	v_lshl_add_u64 v[142:143], v[228:229], 0, s[22:23]
	s_mov_b32 m0, s95
	s_nop 0
	global_load_lds_dwordx4 v[142:143], off
	s_waitcnt vmcnt(8)
	s_waitcnt lgkmcnt(0)
	s_barrier
	s_setprio 1
	s_waitcnt lgkmcnt(0)
	v_mfma_f32_16x16x32_bf16 v[62:65], v[130:133], v[192:195], v[62:65]
	v_mfma_f32_16x16x32_bf16 v[58:61], v[138:141], v[192:195], v[58:61]
	v_mfma_f32_16x16x32_bf16 v[46:49], v[130:133], v[204:207], v[46:49]
	v_mfma_f32_16x16x32_bf16 v[42:45], v[138:141], v[204:207], v[42:45]
	v_mfma_f32_16x16x32_bf16 v[30:33], v[130:133], v[212:215], v[30:33]
	v_mfma_f32_16x16x32_bf16 v[26:29], v[138:141], v[212:215], v[26:29]
	v_mfma_f32_16x16x32_bf16 v[14:17], v[130:133], v[220:223], v[14:17]
	v_mfma_f32_16x16x32_bf16 v[10:13], v[138:141], v[220:223], v[10:13]
	v_mfma_f32_16x16x32_bf16 v[62:65], v[134:137], v[200:203], v[62:65]
	v_mfma_f32_16x16x32_bf16 v[58:61], v[164:167], v[200:203], v[58:61]
	v_mfma_f32_16x16x32_bf16 v[46:49], v[134:137], v[208:211], v[46:49]
	v_mfma_f32_16x16x32_bf16 v[42:45], v[164:167], v[208:211], v[42:45]
	v_mfma_f32_16x16x32_bf16 v[30:33], v[134:137], v[216:219], v[30:33]
	v_mfma_f32_16x16x32_bf16 v[26:29], v[164:167], v[216:219], v[26:29]
	v_mfma_f32_16x16x32_bf16 v[14:17], v[134:137], v[224:227], v[14:17]
	v_mfma_f32_16x16x32_bf16 v[10:13], v[164:167], v[224:227], v[10:13]
	v_mfma_f32_16x16x32_bf16 v[54:57], v[168:171], v[192:195], v[54:57]
	v_mfma_f32_16x16x32_bf16 v[50:53], v[184:187], v[192:195], v[50:53]
	v_mfma_f32_16x16x32_bf16 v[38:41], v[168:171], v[204:207], v[38:41]
	v_mfma_f32_16x16x32_bf16 v[34:37], v[184:187], v[204:207], v[34:37]
	v_mfma_f32_16x16x32_bf16 v[22:25], v[168:171], v[212:215], v[22:25]
	v_mfma_f32_16x16x32_bf16 v[18:21], v[184:187], v[212:215], v[18:21]
	v_mfma_f32_16x16x32_bf16 v[6:9], v[168:171], v[220:223], v[6:9]
	v_mfma_f32_16x16x32_bf16 v[2:5], v[184:187], v[220:223], v[2:5]
	v_mfma_f32_16x16x32_bf16 v[54:57], v[180:183], v[200:203], v[54:57]
	v_mfma_f32_16x16x32_bf16 v[50:53], v[188:191], v[200:203], v[50:53]
	v_mfma_f32_16x16x32_bf16 v[38:41], v[180:183], v[208:211], v[38:41]
	v_mfma_f32_16x16x32_bf16 v[34:37], v[188:191], v[208:211], v[34:37]
	v_mfma_f32_16x16x32_bf16 v[22:25], v[180:183], v[216:219], v[22:25]
	v_mfma_f32_16x16x32_bf16 v[18:21], v[188:191], v[216:219], v[18:21]
	v_mfma_f32_16x16x32_bf16 v[6:9], v[180:183], v[224:227], v[6:9]
	v_mfma_f32_16x16x32_bf16 v[2:5], v[188:191], v[224:227], v[2:5]
	s_setprio 0
	s_barrier
	s_add_i32 s51, s51, 2
	s_add_u32 s4, s4, 0x100
	s_addc_u32 s5, s5, 0
	s_add_u32 s26, s26, 0x100
	s_addc_u32 s27, s27, 0
	s_cmp_gt_u32 s51, 29
	s_cbranch_scc0 .LBB0_206
	s_and_b64 vcc, exec, s[42:43]
	s_cbranch_vccz .LBB0_210
	s_barrier
	v_lshl_add_u32 v130, s70, 8, v151
	s_cmp_gt_i32 s16, 23
	s_mov_b64 s[4:5], -1
	s_cbranch_scc1 .LBB0_211

; #define PG8_STAGE(bufoff, gbase, voff) do { _Pragma("unroll") for (int _i = 0; _i < 2; ++_i) \
;         __builtin_amdgcn_global_load_lds((const unsigned*)((const char*)(gbase) + (voff)[_i]), (PG8_LAS unsigned*)(lds + (bufoff) + ldsw + _i * 8192), 16, 0, 0); } while (0)
; #define PG8_LDA(dst, b, h) do { _Pragma("unroll") for (int m = 0; m < 4; ++m) _Pragma("unroll") for (int k = 0; k < 2; ++k) dst[m][k] = *(const PG8_LAS bf16x8*)(lds + PG8_SA(b, h) + aoff + m * 2048 + k * 1024); } while (0)
; #define PG8_LDB(dst, b, h) do { _Pragma("unroll") for (int n = 0; n < 2; ++n) _Pragma("unroll") for (int k = 0; k < 2; ++k) dst[n][k] = *(const PG8_LAS bf16x8*)(lds + PG8_SB(b, h) + boff + n * 2048 + k * 1024); } while (0)
; #define PG8_MMA(ai, bj, At, Bt) do { __builtin_amdgcn_s_setprio(1); _Pragma("unroll") for (int m = 0; m < 4; ++m) _Pragma("unroll") for (int n = 0; n < 2; ++n) _Pragma("unroll") for (int k = 0; k < 2; ++k) \
;         acc[ai][bj][m][n] = __builtin_amdgcn_mfma_f32_16x16x32_bf16(Bt[n][k], At[m][k], acc[ai][bj][m][n], 0, 0, 0); __builtin_amdgcn_s_setprio(0); } while (0)
; #define PG8_WAIT_V(n) asm volatile("s_waitcnt vmcnt(" #n ")" ::: "memory")
; #define PG8_WAIT_L(n) asm volatile("s_waitcnt lgkmcnt(" #n ")" ::: "memory")
; #define PG8_BAR __builtin_amdgcn_s_barrier()
; #define PG8_SCHED __builtin_amdgcn_sched_barrier(0)
; template <class Epi, class Sched, bool ALIGN_EPI = false, bool SP2 = false, bool MID = false>
; __device__ __forceinline__ void gemm_phase(PG8_LAS unsigned char* lds, const Gemm g, const Sched& S, const Epi& E) {
;     ...
;             PG8_LDB(B0, 0, 0); PG8_LDB(B1, 0, 1); PG8_SCHED; PG8_LDA(At, 0, 0); PG8_STAGE(PG8_SA(1, 1), a1 + hstep, voffA);
;             PG8_WAIT_V(8); PG8_WAIT_L(0); PG8_BAR; PG8_MMA(0, 0, At, B0); PG8_MMA(0, 1, At, B1); PG8_BAR; PG8_SCHED;
;             PG8_LDA(At, 0, 1); PG8_STAGE(PG8_SB(0, 0), b2, voffB); PG8_STAGE(PG8_SB(0, 1), b2 + hstep, voffB); PG8_STAGE(PG8_SA(0, 0), a2, voffA);
;             PG8_WAIT_V(8); PG8_WAIT_L(0); PG8_BAR; PG8_MMA(1, 0, At, B0); PG8_MMA(1, 1, At, B1); PG8_BAR; PG8_SCHED;
.LBB0_1439:
	v_add_u32_e32 v142, s15, v193
	v_add_u32_e32 v175, s81, v193
	s_add_u32 s4, s42, s46
	ds_read_b128 v[130:133], v142
	ds_read_b128 v[134:137], v142 offset:1024
	ds_read_b128 v[138:141], v142 offset:2048
	ds_read_b128 v[142:145], v142 offset:3072
	ds_read_b128 v[146:149], v175
	ds_read_b128 v[150:153], v175 offset:1024
	ds_read_b128 v[154:157], v175 offset:2048
	ds_read_b128 v[184:187], v175 offset:3072
	s_addc_u32 s5, s43, s47
	s_add_u32 s4, s4, 0x100
	s_addc_u32 s5, s5, 0
	s_add_u32 s92, s89, s46
	s_addc_u32 s93, s90, s47
	s_cmpk_eq_i32 s46, 0xf00
	s_cselect_b32 s49, s37, s5
	s_cselect_b32 s48, s87, s4
	s_cselect_b32 s5, s27, s93
	s_cselect_b32 s4, s88, s92
	v_lshl_add_u64 v[196:197], v[180:181], 0, s[46:47]
	s_add_i32 m0, s54, 0xc000
	ds_read_b128 v[188:191], v195
	ds_read_b128 v[200:203], v195 offset:1024
	ds_read_b128 v[204:207], v195 offset:2048
	ds_read_b128 v[208:211], v195 offset:3072
	ds_read_b128 v[212:215], v195 offset:4096
	ds_read_b128 v[216:219], v195 offset:5120
	ds_read_b128 v[220:223], v195 offset:6144
	ds_read_b128 v[224:227], v195 offset:7168
	global_load_lds_dwordx4 v[196:197], off
	v_lshl_add_u64 v[196:197], v[182:183], 0, s[46:47]
	s_add_i32 m0, s54, 0xe000
	s_nop 0
	global_load_lds_dwordx4 v[196:197], off
	s_waitcnt vmcnt(8)
	s_waitcnt lgkmcnt(0)
	s_barrier
	s_setprio 1
	s_waitcnt lgkmcnt(0)
	v_mfma_f32_16x16x32_bf16 v[126:129], v[130:133], v[188:191], v[126:129]
	v_mfma_f32_16x16x32_bf16 v[122:125], v[138:141], v[188:191], v[122:125]
	v_mfma_f32_16x16x32_bf16 v[110:113], v[130:133], v[204:207], v[110:113]
	v_mfma_f32_16x16x32_bf16 v[106:109], v[138:141], v[204:207], v[106:109]
	v_mfma_f32_16x16x32_bf16 v[94:97], v[130:133], v[212:215], v[94:97]
	v_mfma_f32_16x16x32_bf16 v[90:93], v[138:141], v[212:215], v[90:93]
	v_mfma_f32_16x16x32_bf16 v[78:81], v[130:133], v[220:223], v[78:81]
	v_mfma_f32_16x16x32_bf16 v[74:77], v[138:141], v[220:223], v[74:77]
	v_mfma_f32_16x16x32_bf16 v[126:129], v[134:137], v[200:203], v[126:129]
	v_mfma_f32_16x16x32_bf16 v[122:125], v[142:145], v[200:203], v[122:125]
	v_mfma_f32_16x16x32_bf16 v[110:113], v[134:137], v[208:211], v[110:113]
	v_mfma_f32_16x16x32_bf16 v[106:109], v[142:145], v[208:211], v[106:109]
	v_mfma_f32_16x16x32_bf16 v[94:97], v[134:137], v[216:219], v[94:97]
	v_mfma_f32_16x16x32_bf16 v[90:93], v[142:145], v[216:219], v[90:93]
	v_mfma_f32_16x16x32_bf16 v[78:81], v[134:137], v[224:227], v[78:81]
	v_mfma_f32_16x16x32_bf16 v[74:77], v[142:145], v[224:227], v[74:77]
	v_mfma_f32_16x16x32_bf16 v[118:121], v[146:149], v[188:191], v[118:121]
	v_mfma_f32_16x16x32_bf16 v[114:117], v[154:157], v[188:191], v[114:117]
	v_mfma_f32_16x16x32_bf16 v[102:105], v[146:149], v[204:207], v[102:105]
	v_mfma_f32_16x16x32_bf16 v[98:101], v[154:157], v[204:207], v[98:101]
	v_mfma_f32_16x16x32_bf16 v[86:89], v[146:149], v[212:215], v[86:89]
	v_mfma_f32_16x16x32_bf16 v[82:85], v[154:157], v[212:215], v[82:85]
	v_mfma_f32_16x16x32_bf16 v[70:73], v[146:149], v[220:223], v[70:73]
	v_mfma_f32_16x16x32_bf16 v[66:69], v[154:157], v[220:223], v[66:69]
	v_mfma_f32_16x16x32_bf16 v[118:121], v[150:153], v[200:203], v[118:121]
	v_mfma_f32_16x16x32_bf16 v[114:117], v[184:187], v[200:203], v[114:117]
	v_mfma_f32_16x16x32_bf16 v[102:105], v[150:153], v[208:211], v[102:105]
	v_mfma_f32_16x16x32_bf16 v[98:101], v[184:187], v[208:211], v[98:101]
	v_mfma_f32_16x16x32_bf16 v[86:89], v[150:153], v[216:219], v[86:89]
	v_mfma_f32_16x16x32_bf16 v[82:85], v[184:187], v[216:219], v[82:85]
	v_mfma_f32_16x16x32_bf16 v[70:73], v[150:153], v[224:227], v[70:73]
	v_mfma_f32_16x16x32_bf16 v[66:69], v[184:187], v[224:227], v[66:69]
	s_setprio 0
	s_barrier
	s_add_i32 s92, s15, s53
	v_lshl_add_u64 v[196:197], s[4:5], 0, v[160:161]
	s_mov_b32 m0, s92
	ds_read_b128 v[188:191], v195 offset:16384
	ds_read_b128 v[200:203], v195 offset:17408
	ds_read_b128 v[204:207], v195 offset:18432
	ds_read_b128 v[208:211], v195 offset:19456
	ds_read_b128 v[212:215], v195 offset:20480
	ds_read_b128 v[216:219], v195 offset:21504
	ds_read_b128 v[220:223], v195 offset:22528
	ds_read_b128 v[224:227], v195 offset:23552
	global_load_lds_dwordx4 v[196:197], off
	s_add_i32 m0, s92, 0x2000
	s_add_u32 s92, s4, 0x80000
	v_lshl_add_u64 v[228:229], s[4:5], 0, v[164:165]
	s_addc_u32 s93, s5, 0
	s_add_i32 s94, s81, s53
	global_load_lds_dwordx4 v[228:229], off
	v_lshl_add_u64 v[230:231], s[92:93], 0, v[160:161]
	s_mov_b32 m0, s94
	v_lshl_add_u64 v[232:233], s[48:49], 0, v[162:163]
	global_load_lds_dwordx4 v[230:231], off
	v_lshl_add_u64 v[230:231], s[92:93], 0, v[164:165]
	s_add_i32 m0, s94, 0x2000
	s_nop 0
	global_load_lds_dwordx4 v[230:231], off
	v_lshl_add_u64 v[230:231], s[48:49], 0, v[158:159]
	s_mov_b32 m0, s54
	s_nop 0
	global_load_lds_dwordx4 v[230:231], off
	s_mov_b32 m0, s55
	s_nop 0
	global_load_lds_dwordx4 v[232:233], off
	s_waitcnt vmcnt(8)
	s_waitcnt lgkmcnt(0)
	s_barrier
; #define PG8_STAGE(bufoff, gbase, voff) do { _Pragma("unroll") for (int _i = 0; _i < 2; ++_i) \
;         __builtin_amdgcn_global_load_lds((const unsigned*)((const char*)(gbase) + (voff)[_i]), (PG8_LAS unsigned*)(lds + (bufoff) + ldsw + _i * 8192), 16, 0, 0); } while (0)
; #define PG8_LDA(dst, b, h) do { _Pragma("unroll") for (int m = 0; m < 4; ++m) _Pragma("unroll") for (int k = 0; k < 2; ++k) dst[m][k] = *(const PG8_LAS bf16x8*)(lds + PG8_SA(b, h) + aoff + m * 2048 + k * 1024); } while (0)
; #define PG8_LDB(dst, b, h) do { _Pragma("unroll") for (int n = 0; n < 2; ++n) _Pragma("unroll") for (int k = 0; k < 2; ++k) dst[n][k] = *(const PG8_LAS bf16x8*)(lds + PG8_SB(b, h) + boff + n * 2048 + k * 1024); } while (0)
; #define PG8_MMA(ai, bj, At, Bt) do { __builtin_amdgcn_s_setprio(1); _Pragma("unroll") for (int m = 0; m < 4; ++m) _Pragma("unroll") for (int n = 0; n < 2; ++n) _Pragma("unroll") for (int k = 0; k < 2; ++k) \
;         acc[ai][bj][m][n] = __builtin_amdgcn_mfma_f32_16x16x32_bf16(Bt[n][k], At[m][k], acc[ai][bj][m][n], 0, 0, 0); __builtin_amdgcn_s_setprio(0); } while (0)
; #define PG8_WAIT_V(n) asm volatile("s_waitcnt vmcnt(" #n ")" ::: "memory")
; #define PG8_WAIT_L(n) asm volatile("s_waitcnt lgkmcnt(" #n ")" ::: "memory")
; #define PG8_BAR __builtin_amdgcn_s_barrier()
; #define PG8_SCHED __builtin_amdgcn_sched_barrier(0)
; template <class Epi, class Sched, bool ALIGN_EPI = false, bool SP2 = false, bool MID = false>
; __device__ __forceinline__ void gemm_phase(PG8_LAS unsigned char* lds, const Gemm g, const Sched& S, const Epi& E) {
;     ...
;             PG8_WAIT_V(8); PG8_WAIT_L(0); PG8_BAR; PG8_MMA(1, 0, At, B0); PG8_MMA(1, 1, At, B1); PG8_BAR; PG8_SCHED;
;             PG8_LDB(B0, 1, 0); PG8_LDB(B1, 1, 1); PG8_SCHED; PG8_LDA(At, 1, 0); PG8_STAGE(PG8_SA(0, 1), a2 + hstep, voffA);
;             PG8_WAIT_V(8); PG8_WAIT_L(0); PG8_BAR; PG8_MMA(0, 0, At, B0); PG8_MMA(0, 1, At, B1); PG8_BAR; PG8_SCHED;
	s_setprio 1
	s_waitcnt lgkmcnt(0)
	v_mfma_f32_16x16x32_bf16 v[62:65], v[130:133], v[188:191], v[62:65]
	v_mfma_f32_16x16x32_bf16 v[58:61], v[138:141], v[188:191], v[58:61]
	v_mfma_f32_16x16x32_bf16 v[46:49], v[130:133], v[204:207], v[46:49]
	v_mfma_f32_16x16x32_bf16 v[42:45], v[138:141], v[204:207], v[42:45]
	v_mfma_f32_16x16x32_bf16 v[30:33], v[130:133], v[212:215], v[30:33]
	v_mfma_f32_16x16x32_bf16 v[26:29], v[138:141], v[212:215], v[26:29]
	v_mfma_f32_16x16x32_bf16 v[14:17], v[130:133], v[220:223], v[14:17]
	v_mfma_f32_16x16x32_bf16 v[10:13], v[138:141], v[220:223], v[10:13]
	v_mfma_f32_16x16x32_bf16 v[62:65], v[134:137], v[200:203], v[62:65]
	v_mfma_f32_16x16x32_bf16 v[58:61], v[142:145], v[200:203], v[58:61]
	v_mfma_f32_16x16x32_bf16 v[46:49], v[134:137], v[208:211], v[46:49]
	v_mfma_f32_16x16x32_bf16 v[42:45], v[142:145], v[208:211], v[42:45]
	v_mfma_f32_16x16x32_bf16 v[30:33], v[134:137], v[216:219], v[30:33]
	v_mfma_f32_16x16x32_bf16 v[26:29], v[142:145], v[216:219], v[26:29]
	v_mfma_f32_16x16x32_bf16 v[14:17], v[134:137], v[224:227], v[14:17]
	v_mfma_f32_16x16x32_bf16 v[10:13], v[142:145], v[224:227], v[10:13]
	v_mfma_f32_16x16x32_bf16 v[54:57], v[146:149], v[188:191], v[54:57]
	v_mfma_f32_16x16x32_bf16 v[50:53], v[154:157], v[188:191], v[50:53]
	v_mfma_f32_16x16x32_bf16 v[38:41], v[146:149], v[204:207], v[38:41]
	v_mfma_f32_16x16x32_bf16 v[34:37], v[154:157], v[204:207], v[34:37]
	v_mfma_f32_16x16x32_bf16 v[22:25], v[146:149], v[212:215], v[22:25]
	v_mfma_f32_16x16x32_bf16 v[18:21], v[154:157], v[212:215], v[18:21]
	v_mfma_f32_16x16x32_bf16 v[6:9], v[146:149], v[220:223], v[6:9]
	v_mfma_f32_16x16x32_bf16 v[2:5], v[154:157], v[220:223], v[2:5]
	v_mfma_f32_16x16x32_bf16 v[54:57], v[150:153], v[200:203], v[54:57]
	v_mfma_f32_16x16x32_bf16 v[50:53], v[184:187], v[200:203], v[50:53]
	v_mfma_f32_16x16x32_bf16 v[38:41], v[150:153], v[208:211], v[38:41]
	v_mfma_f32_16x16x32_bf16 v[34:37], v[184:187], v[208:211], v[34:37]
	v_mfma_f32_16x16x32_bf16 v[22:25], v[150:153], v[216:219], v[22:25]
	v_mfma_f32_16x16x32_bf16 v[18:21], v[184:187], v[216:219], v[18:21]
	v_mfma_f32_16x16x32_bf16 v[6:9], v[150:153], v[224:227], v[6:9]
	v_mfma_f32_16x16x32_bf16 v[2:5], v[184:187], v[224:227], v[2:5]
	s_setprio 0
	s_barrier
	s_add_i32 s92, 0, 0x18000
	s_add_i32 s93, 0, 0x1c000
	v_add_u32_e32 v142, s92, v193
	v_add_u32_e32 v175, s93, v193
	ds_read_b128 v[130:133], v142
	ds_read_b128 v[134:137], v142 offset:1024
	ds_read_b128 v[138:141], v142 offset:2048
	ds_read_b128 v[142:145], v142 offset:3072
	ds_read_b128 v[146:149], v175
	ds_read_b128 v[150:153], v175 offset:1024
	ds_read_b128 v[154:157], v175 offset:2048
	ds_read_b128 v[184:187], v175 offset:3072
	s_add_u32 s48, s48, 0x80000
	s_addc_u32 s49, s49, 0
	s_mov_b32 m0, s56
	v_lshl_add_u64 v[234:235], s[48:49], 0, v[158:159]
	ds_read_b128 v[188:191], v195 offset:32768
	ds_read_b128 v[200:203], v195 offset:33792
	ds_read_b128 v[204:207], v195 offset:34816
	ds_read_b128 v[208:211], v195 offset:35840
	ds_read_b128 v[212:215], v195 offset:36864
	ds_read_b128 v[216:219], v195 offset:37888
	ds_read_b128 v[220:223], v195 offset:38912
	ds_read_b128 v[224:227], v195 offset:39936
	global_load_lds_dwordx4 v[234:235], off
	v_lshl_add_u64 v[234:235], s[48:49], 0, v[162:163]
	s_mov_b32 m0, s57
	s_nop 0
	global_load_lds_dwordx4 v[234:235], off
	s_waitcnt vmcnt(8)
	s_waitcnt lgkmcnt(0)
	s_barrier
	s_setprio 1
	s_waitcnt lgkmcnt(0)
	v_mfma_f32_16x16x32_bf16 v[126:129], v[130:133], v[188:191], v[126:129]
	v_mfma_f32_16x16x32_bf16 v[122:125], v[138:141], v[188:191], v[122:125]
	v_mfma_f32_16x16x32_bf16 v[110:113], v[130:133], v[204:207], v[110:113]
	v_mfma_f32_16x16x32_bf16 v[106:109], v[138:141], v[204:207], v[106:109]
	v_mfma_f32_16x16x32_bf16 v[94:97], v[130:133], v[212:215], v[94:97]
	v_mfma_f32_16x16x32_bf16 v[90:93], v[138:141], v[212:215], v[90:93]
	v_mfma_f32_16x16x32_bf16 v[78:81], v[130:133], v[220:223], v[78:81]
	v_mfma_f32_16x16x32_bf16 v[74:77], v[138:141], v[220:223], v[74:77]
	v_mfma_f32_16x16x32_bf16 v[126:129], v[134:137], v[200:203], v[126:129]
	v_mfma_f32_16x16x32_bf16 v[122:125], v[142:145], v[200:203], v[122:125]
	v_mfma_f32_16x16x32_bf16 v[110:113], v[134:137], v[208:211], v[110:113]
	v_mfma_f32_16x16x32_bf16 v[106:109], v[142:145], v[208:211], v[106:109]
	v_mfma_f32_16x16x32_bf16 v[94:97], v[134:137], v[216:219], v[94:97]
	v_mfma_f32_16x16x32_bf16 v[90:93], v[142:145], v[216:219], v[90:93]
	v_mfma_f32_16x16x32_bf16 v[78:81], v[134:137], v[224:227], v[78:81]
	v_mfma_f32_16x16x32_bf16 v[74:77], v[142:145], v[224:227], v[74:77]
	v_mfma_f32_16x16x32_bf16 v[118:121], v[146:149], v[188:191], v[118:121]
	v_mfma_f32_16x16x32_bf16 v[114:117], v[154:157], v[188:191], v[114:117]
	v_mfma_f32_16x16x32_bf16 v[102:105], v[146:149], v[204:207], v[102:105]
	v_mfma_f32_16x16x32_bf16 v[98:101], v[154:157], v[204:207], v[98:101]
	v_mfma_f32_16x16x32_bf16 v[86:89], v[146:149], v[212:215], v[86:89]
	v_mfma_f32_16x16x32_bf16 v[82:85], v[154:157], v[212:215], v[82:85]
	v_mfma_f32_16x16x32_bf16 v[70:73], v[146:149], v[220:223], v[70:73]
	v_mfma_f32_16x16x32_bf16 v[66:69], v[154:157], v[220:223], v[66:69]
	v_mfma_f32_16x16x32_bf16 v[118:121], v[150:153], v[200:203], v[118:121]
	v_mfma_f32_16x16x32_bf16 v[114:117], v[184:187], v[200:203], v[114:117]
	v_mfma_f32_16x16x32_bf16 v[102:105], v[150:153], v[208:211], v[102:105]
	v_mfma_f32_16x16x32_bf16 v[98:101], v[184:187], v[208:211], v[98:101]
	v_mfma_f32_16x16x32_bf16 v[86:89], v[150:153], v[216:219], v[86:89]
	v_mfma_f32_16x16x32_bf16 v[82:85], v[184:187], v[216:219], v[82:85]
	v_mfma_f32_16x16x32_bf16 v[70:73], v[150:153], v[224:227], v[70:73]
	v_mfma_f32_16x16x32_bf16 v[66:69], v[184:187], v[224:227], v[66:69]
	s_setprio 0
	s_barrier
; #define PG8_STAGE(bufoff, gbase, voff) do { _Pragma("unroll") for (int _i = 0; _i < 2; ++_i) \
;         __builtin_amdgcn_global_load_lds((const unsigned*)((const char*)(gbase) + (voff)[_i]), (PG8_LAS unsigned*)(lds + (bufoff) + ldsw + _i * 8192), 16, 0, 0); } while (0)
; #define PG8_LDA(dst, b, h) do { _Pragma("unroll") for (int m = 0; m < 4; ++m) _Pragma("unroll") for (int k = 0; k < 2; ++k) dst[m][k] = *(const PG8_LAS bf16x8*)(lds + PG8_SA(b, h) + aoff + m * 2048 + k * 1024); } while (0)
; #define PG8_MMA(ai, bj, At, Bt) do { __builtin_amdgcn_s_setprio(1); _Pragma("unroll") for (int m = 0; m < 4; ++m) _Pragma("unroll") for (int n = 0; n < 2; ++n) _Pragma("unroll") for (int k = 0; k < 2; ++k) \
;         acc[ai][bj][m][n] = __builtin_amdgcn_mfma_f32_16x16x32_bf16(Bt[n][k], At[m][k], acc[ai][bj][m][n], 0, 0, 0); __builtin_amdgcn_s_setprio(0); } while (0)
; #define PG8_WAIT_V(n) asm volatile("s_waitcnt vmcnt(" #n ")" ::: "memory")
; #define PG8_WAIT_L(n) asm volatile("s_waitcnt lgkmcnt(" #n ")" ::: "memory")
; #define PG8_BAR __builtin_amdgcn_s_barrier()
; #define PG8_SCHED __builtin_amdgcn_sched_barrier(0)
; template <class Epi, class Sched, bool ALIGN_EPI = false, bool SP2 = false, bool MID = false>
; __device__ __forceinline__ void gemm_phase(PG8_LAS unsigned char* lds, const Gemm g, const Sched& S, const Epi& E) {
;     ...
;             PG8_LDA(At, 1, 1); PG8_STAGE(PG8_SB(1, 0), b3, voffB); PG8_STAGE(PG8_SB(1, 1), b3 + hstep, voffB); PG8_STAGE(PG8_SA(1, 0), a3, voffA);
;             PG8_WAIT_V(8); PG8_WAIT_L(0); PG8_BAR; PG8_MMA(1, 0, At, B0); PG8_MMA(1, 1, At, B1); PG8_BAR; PG8_SCHED;
	s_add_i32 s48, s92, s53
	v_lshl_add_u64 v[196:197], v[196:197], 0, s[20:21]
	s_mov_b32 m0, s48
	ds_read_b128 v[188:191], v195 offset:49152
	ds_read_b128 v[200:203], v195 offset:50176
	ds_read_b128 v[204:207], v195 offset:51200
	ds_read_b128 v[208:211], v195 offset:52224
	ds_read_b128 v[212:215], v195 offset:53248
	ds_read_b128 v[216:219], v195 offset:54272
	ds_read_b128 v[220:223], v195 offset:55296
	ds_read_b128 v[224:227], v195 offset:56320
	global_load_lds_dwordx4 v[196:197], off
	s_add_i32 m0, s48, 0x2000
	s_add_u32 s4, s4, 0x80080
	v_lshl_add_u64 v[196:197], v[228:229], 0, s[20:21]
	s_addc_u32 s5, s5, 0
	s_add_i32 s48, s93, s53
	global_load_lds_dwordx4 v[196:197], off
	v_lshl_add_u64 v[196:197], s[4:5], 0, v[160:161]
	s_mov_b32 m0, s48
	s_nop 0
	global_load_lds_dwordx4 v[196:197], off
	v_lshl_add_u64 v[196:197], s[4:5], 0, v[164:165]
	s_add_i32 m0, s48, 0x2000
	s_nop 0
	global_load_lds_dwordx4 v[196:197], off
	v_lshl_add_u64 v[196:197], v[230:231], 0, s[20:21]
	s_mov_b32 m0, s59
	s_nop 0
	global_load_lds_dwordx4 v[196:197], off
	v_lshl_add_u64 v[196:197], v[232:233], 0, s[20:21]
	s_mov_b32 m0, s62
	s_nop 0
	global_load_lds_dwordx4 v[196:197], off
	s_waitcnt vmcnt(8)
	s_waitcnt lgkmcnt(0)
	s_barrier
	s_setprio 1
	s_waitcnt lgkmcnt(0)
	v_mfma_f32_16x16x32_bf16 v[62:65], v[130:133], v[188:191], v[62:65]
	v_mfma_f32_16x16x32_bf16 v[58:61], v[138:141], v[188:191], v[58:61]
	v_mfma_f32_16x16x32_bf16 v[46:49], v[130:133], v[204:207], v[46:49]
	v_mfma_f32_16x16x32_bf16 v[42:45], v[138:141], v[204:207], v[42:45]
	v_mfma_f32_16x16x32_bf16 v[30:33], v[130:133], v[212:215], v[30:33]
	v_mfma_f32_16x16x32_bf16 v[26:29], v[138:141], v[212:215], v[26:29]
	v_mfma_f32_16x16x32_bf16 v[14:17], v[130:133], v[220:223], v[14:17]
	v_mfma_f32_16x16x32_bf16 v[10:13], v[138:141], v[220:223], v[10:13]
	v_mfma_f32_16x16x32_bf16 v[62:65], v[134:137], v[200:203], v[62:65]
	v_mfma_f32_16x16x32_bf16 v[58:61], v[142:145], v[200:203], v[58:61]
	v_mfma_f32_16x16x32_bf16 v[46:49], v[134:137], v[208:211], v[46:49]
	v_mfma_f32_16x16x32_bf16 v[42:45], v[142:145], v[208:211], v[42:45]
	v_mfma_f32_16x16x32_bf16 v[30:33], v[134:137], v[216:219], v[30:33]
	v_mfma_f32_16x16x32_bf16 v[26:29], v[142:145], v[216:219], v[26:29]
	v_mfma_f32_16x16x32_bf16 v[14:17], v[134:137], v[224:227], v[14:17]
	v_mfma_f32_16x16x32_bf16 v[10:13], v[142:145], v[224:227], v[10:13]
	v_mfma_f32_16x16x32_bf16 v[54:57], v[146:149], v[188:191], v[54:57]
	v_mfma_f32_16x16x32_bf16 v[50:53], v[154:157], v[188:191], v[50:53]
	v_mfma_f32_16x16x32_bf16 v[38:41], v[146:149], v[204:207], v[38:41]
	v_mfma_f32_16x16x32_bf16 v[34:37], v[154:157], v[204:207], v[34:37]
	v_mfma_f32_16x16x32_bf16 v[22:25], v[146:149], v[212:215], v[22:25]
	v_mfma_f32_16x16x32_bf16 v[18:21], v[154:157], v[212:215], v[18:21]
	v_mfma_f32_16x16x32_bf16 v[6:9], v[146:149], v[220:223], v[6:9]
	v_mfma_f32_16x16x32_bf16 v[2:5], v[154:157], v[220:223], v[2:5]
	v_mfma_f32_16x16x32_bf16 v[54:57], v[150:153], v[200:203], v[54:57]
	v_mfma_f32_16x16x32_bf16 v[50:53], v[184:187], v[200:203], v[50:53]
	v_mfma_f32_16x16x32_bf16 v[38:41], v[150:153], v[208:211], v[38:41]
	v_mfma_f32_16x16x32_bf16 v[34:37], v[184:187], v[208:211], v[34:37]
	v_mfma_f32_16x16x32_bf16 v[22:25], v[150:153], v[216:219], v[22:25]
	v_mfma_f32_16x16x32_bf16 v[18:21], v[184:187], v[216:219], v[18:21]
	v_mfma_f32_16x16x32_bf16 v[6:9], v[150:153], v[224:227], v[6:9]
	v_mfma_f32_16x16x32_bf16 v[2:5], v[184:187], v[224:227], v[2:5]
	s_setprio 0
	s_barrier
	s_add_i32 s91, s91, 2
	s_add_u32 s46, s46, 0x100
	s_addc_u32 s47, s47, 0
	s_cmp_gt_u32 s91, 29
	s_cbranch_scc1 .LBB0_1442

; #define PG8_STAGE(bufoff, gbase, voff) do { _Pragma("unroll") for (int _i = 0; _i < 2; ++_i) \
;         __builtin_amdgcn_global_load_lds((const unsigned*)((const char*)(gbase) + (voff)[_i]), (PG8_LAS unsigned*)(lds + (bufoff) + ldsw + _i * 8192), 16, 0, 0); } while (0)
; #define PG8_LDA(dst, b, h) do { _Pragma("unroll") for (int m = 0; m < 4; ++m) _Pragma("unroll") for (int k = 0; k < 2; ++k) dst[m][k] = *(const PG8_LAS bf16x8*)(lds + PG8_SA(b, h) + aoff + m * 2048 + k * 1024); } while (0)
; #define PG8_LDB(dst, b, h) do { _Pragma("unroll") for (int n = 0; n < 2; ++n) _Pragma("unroll") for (int k = 0; k < 2; ++k) dst[n][k] = *(const PG8_LAS bf16x8*)(lds + PG8_SB(b, h) + boff + n * 2048 + k * 1024); } while (0)
; #define PG8_MMA(ai, bj, At, Bt) do { __builtin_amdgcn_s_setprio(1); _Pragma("unroll") for (int m = 0; m < 4; ++m) _Pragma("unroll") for (int n = 0; n < 2; ++n) _Pragma("unroll") for (int k = 0; k < 2; ++k) \
;         acc[ai][bj][m][n] = __builtin_amdgcn_mfma_f32_16x16x32_bf16(Bt[n][k], At[m][k], acc[ai][bj][m][n], 0, 0, 0); __builtin_amdgcn_s_setprio(0); } while (0)
; #define PG8_WAIT_V(n) asm volatile("s_waitcnt vmcnt(" #n ")" ::: "memory")
; #define PG8_WAIT_L(n) asm volatile("s_waitcnt lgkmcnt(" #n ")" ::: "memory")
; #define PG8_BAR __builtin_amdgcn_s_barrier()
; #define PG8_SCHED __builtin_amdgcn_sched_barrier(0)
; template <class Epi, class Sched, bool ALIGN_EPI = false, bool SP2 = false, bool MID = false>
; __device__ __forceinline__ void gemm_phase(PG8_LAS unsigned char* lds, const Gemm g, const Sched& S, const Epi& E) {
;     ...
;             PG8_LDB(B0, 0, 0); PG8_LDB(B1, 0, 1); PG8_SCHED; PG8_LDA(At, 0, 0); PG8_STAGE(PG8_SA(1, 1), a1 + hstep, voffA);
;             PG8_WAIT_V(8); PG8_WAIT_L(0); PG8_BAR; PG8_MMA(0, 0, At, B0); PG8_MMA(0, 1, At, B1); PG8_BAR; PG8_SCHED;
;             PG8_LDA(At, 0, 1); PG8_STAGE(PG8_SB(0, 0), b2, voffB); PG8_STAGE(PG8_SB(0, 1), b2 + hstep, voffB); PG8_STAGE(PG8_SA(0, 0), a2, voffA);
;             PG8_WAIT_V(8); PG8_WAIT_L(0); PG8_BAR; PG8_MMA(1, 0, At, B0); PG8_MMA(1, 1, At, B1); PG8_BAR; PG8_SCHED;
.LBB0_1528:
	ds_read_b128 v[152:155], v149
	ds_read_b128 v[156:159], v149 offset:1024
	ds_read_b128 v[160:163], v149 offset:2048
	ds_read_b128 v[164:167], v149 offset:3072
	ds_read_b128 v[168:171], v150
	ds_read_b128 v[172:175], v150 offset:1024
	ds_read_b128 v[176:179], v150 offset:2048
	ds_read_b128 v[180:183], v150 offset:3072
	s_add_u32 s50, s48, 0xfff80080
	s_addc_u32 s51, s49, -1
	s_cmp_eq_u32 s81, 28
	s_cselect_b32 s55, s41, s51
	s_cselect_b32 s54, s77, s50
	s_cselect_b32 s51, s39, s80
	s_cselect_b32 s50, s78, s79
	v_lshl_add_u64 v[196:197], s[48:49], 0, v[138:139]
	s_add_i32 m0, s37, 0xc000
	ds_read_b128 v[184:187], v151
	ds_read_b128 v[188:191], v151 offset:1024
	ds_read_b128 v[192:195], v151 offset:2048
	ds_read_b128 v[200:203], v151 offset:3072
	ds_read_b128 v[204:207], v151 offset:4096
	ds_read_b128 v[208:211], v151 offset:5120
	ds_read_b128 v[212:215], v151 offset:6144
	ds_read_b128 v[216:219], v151 offset:7168
	global_load_lds_dwordx4 v[196:197], off
	v_lshl_add_u64 v[196:197], s[48:49], 0, v[140:141]
	s_add_i32 m0, s37, 0xe000
	s_nop 0
	global_load_lds_dwordx4 v[196:197], off
	s_waitcnt vmcnt(8)
	s_waitcnt lgkmcnt(0)
	s_barrier
	s_setprio 1
	s_waitcnt lgkmcnt(0)
	v_mfma_f32_16x16x32_bf16 v[126:129], v[152:155], v[184:187], v[126:129]
	v_mfma_f32_16x16x32_bf16 v[122:125], v[160:163], v[184:187], v[122:125]
	v_mfma_f32_16x16x32_bf16 v[118:121], v[152:155], v[192:195], v[118:121]
	v_mfma_f32_16x16x32_bf16 v[114:117], v[160:163], v[192:195], v[114:117]
	v_mfma_f32_16x16x32_bf16 v[102:105], v[152:155], v[204:207], v[102:105]
	v_mfma_f32_16x16x32_bf16 v[98:101], v[160:163], v[204:207], v[98:101]
	v_mfma_f32_16x16x32_bf16 v[86:89], v[152:155], v[212:215], v[86:89]
	v_mfma_f32_16x16x32_bf16 v[82:85], v[160:163], v[212:215], v[82:85]
	v_mfma_f32_16x16x32_bf16 v[126:129], v[156:159], v[188:191], v[126:129]
	v_mfma_f32_16x16x32_bf16 v[122:125], v[164:167], v[188:191], v[122:125]
	v_mfma_f32_16x16x32_bf16 v[118:121], v[156:159], v[200:203], v[118:121]
	v_mfma_f32_16x16x32_bf16 v[114:117], v[164:167], v[200:203], v[114:117]
	v_mfma_f32_16x16x32_bf16 v[102:105], v[156:159], v[208:211], v[102:105]
	v_mfma_f32_16x16x32_bf16 v[98:101], v[164:167], v[208:211], v[98:101]
	v_mfma_f32_16x16x32_bf16 v[86:89], v[156:159], v[216:219], v[86:89]
	v_mfma_f32_16x16x32_bf16 v[82:85], v[164:167], v[216:219], v[82:85]
	v_mfma_f32_16x16x32_bf16 v[110:113], v[168:171], v[184:187], v[110:113]
	v_mfma_f32_16x16x32_bf16 v[106:109], v[176:179], v[184:187], v[106:109]
	v_mfma_f32_16x16x32_bf16 v[94:97], v[168:171], v[192:195], v[94:97]
	v_mfma_f32_16x16x32_bf16 v[90:93], v[176:179], v[192:195], v[90:93]
	v_mfma_f32_16x16x32_bf16 v[78:81], v[168:171], v[204:207], v[78:81]
	v_mfma_f32_16x16x32_bf16 v[74:77], v[176:179], v[204:207], v[74:77]
	v_mfma_f32_16x16x32_bf16 v[70:73], v[168:171], v[212:215], v[70:73]
	v_mfma_f32_16x16x32_bf16 v[66:69], v[176:179], v[212:215], v[66:69]
	v_mfma_f32_16x16x32_bf16 v[110:113], v[172:175], v[188:191], v[110:113]
	v_mfma_f32_16x16x32_bf16 v[106:109], v[180:183], v[188:191], v[106:109]
	v_mfma_f32_16x16x32_bf16 v[94:97], v[172:175], v[200:203], v[94:97]
	v_mfma_f32_16x16x32_bf16 v[90:93], v[180:183], v[200:203], v[90:93]
	v_mfma_f32_16x16x32_bf16 v[78:81], v[172:175], v[208:211], v[78:81]
	v_mfma_f32_16x16x32_bf16 v[74:77], v[180:183], v[208:211], v[74:77]
	v_mfma_f32_16x16x32_bf16 v[70:73], v[172:175], v[216:219], v[70:73]
	v_mfma_f32_16x16x32_bf16 v[66:69], v[180:183], v[216:219], v[66:69]
	s_setprio 0
	s_barrier
	s_add_i32 s82, s70, s15
	v_lshl_add_u64 v[196:197], s[50:51], 0, v[132:133]
	s_mov_b32 m0, s82
	ds_read_b128 v[184:187], v151 offset:16384
	ds_read_b128 v[188:191], v151 offset:17408
	ds_read_b128 v[192:195], v151 offset:18432
	ds_read_b128 v[200:203], v151 offset:19456
	ds_read_b128 v[204:207], v151 offset:20480
	ds_read_b128 v[208:211], v151 offset:21504
	ds_read_b128 v[212:215], v151 offset:22528
	ds_read_b128 v[216:219], v151 offset:23552
	global_load_lds_dwordx4 v[196:197], off
	s_add_i32 m0, s82, 0x2000
	s_add_u32 s82, s50, 0x80000
	v_lshl_add_u64 v[220:221], s[50:51], 0, v[136:137]
	s_addc_u32 s83, s51, 0
	s_add_i32 s84, s71, s15
	global_load_lds_dwordx4 v[220:221], off
	v_lshl_add_u64 v[222:223], s[82:83], 0, v[132:133]
	s_mov_b32 m0, s84
	v_lshl_add_u64 v[224:225], s[54:55], 0, v[134:135]
	global_load_lds_dwordx4 v[222:223], off
	v_lshl_add_u64 v[222:223], s[82:83], 0, v[136:137]
	s_add_i32 m0, s84, 0x2000
	s_nop 0
	global_load_lds_dwordx4 v[222:223], off
	v_lshl_add_u64 v[222:223], s[54:55], 0, v[130:131]
	s_mov_b32 m0, s37
	s_nop 0
	global_load_lds_dwordx4 v[222:223], off
	s_mov_b32 m0, s52
	s_nop 0
	global_load_lds_dwordx4 v[224:225], off
	s_waitcnt vmcnt(8)
	s_waitcnt lgkmcnt(0)
	s_barrier
; #define PG8_STAGE(bufoff, gbase, voff) do { _Pragma("unroll") for (int _i = 0; _i < 2; ++_i) \
;         __builtin_amdgcn_global_load_lds((const unsigned*)((const char*)(gbase) + (voff)[_i]), (PG8_LAS unsigned*)(lds + (bufoff) + ldsw + _i * 8192), 16, 0, 0); } while (0)
; #define PG8_LDA(dst, b, h) do { _Pragma("unroll") for (int m = 0; m < 4; ++m) _Pragma("unroll") for (int k = 0; k < 2; ++k) dst[m][k] = *(const PG8_LAS bf16x8*)(lds + PG8_SA(b, h) + aoff + m * 2048 + k * 1024); } while (0)
; #define PG8_LDB(dst, b, h) do { _Pragma("unroll") for (int n = 0; n < 2; ++n) _Pragma("unroll") for (int k = 0; k < 2; ++k) dst[n][k] = *(const PG8_LAS bf16x8*)(lds + PG8_SB(b, h) + boff + n * 2048 + k * 1024); } while (0)
; #define PG8_MMA(ai, bj, At, Bt) do { __builtin_amdgcn_s_setprio(1); _Pragma("unroll") for (int m = 0; m < 4; ++m) _Pragma("unroll") for (int n = 0; n < 2; ++n) _Pragma("unroll") for (int k = 0; k < 2; ++k) \
;         acc[ai][bj][m][n] = __builtin_amdgcn_mfma_f32_16x16x32_bf16(Bt[n][k], At[m][k], acc[ai][bj][m][n], 0, 0, 0); __builtin_amdgcn_s_setprio(0); } while (0)
; #define PG8_WAIT_V(n) asm volatile("s_waitcnt vmcnt(" #n ")" ::: "memory")
; #define PG8_WAIT_L(n) asm volatile("s_waitcnt lgkmcnt(" #n ")" ::: "memory")
; #define PG8_BAR __builtin_amdgcn_s_barrier()
; #define PG8_SCHED __builtin_amdgcn_sched_barrier(0)
; template <class Epi, class Sched, bool ALIGN_EPI = false, bool SP2 = false, bool MID = false>
; __device__ __forceinline__ void gemm_phase(PG8_LAS unsigned char* lds, const Gemm g, const Sched& S, const Epi& E) {
;     ...
;             PG8_WAIT_V(8); PG8_WAIT_L(0); PG8_BAR; PG8_MMA(1, 0, At, B0); PG8_MMA(1, 1, At, B1); PG8_BAR; PG8_SCHED;
;             PG8_LDB(B0, 1, 0); PG8_LDB(B1, 1, 1); PG8_SCHED; PG8_LDA(At, 1, 0); PG8_STAGE(PG8_SA(0, 1), a2 + hstep, voffA);
;             PG8_WAIT_V(8); PG8_WAIT_L(0); PG8_BAR; PG8_MMA(0, 0, At, B0); PG8_MMA(0, 1, At, B1); PG8_BAR; PG8_SCHED;
	s_setprio 1
	s_waitcnt lgkmcnt(0)
	v_mfma_f32_16x16x32_bf16 v[62:65], v[152:155], v[184:187], v[62:65]
	v_mfma_f32_16x16x32_bf16 v[58:61], v[160:163], v[184:187], v[58:61]
	v_mfma_f32_16x16x32_bf16 v[54:57], v[152:155], v[192:195], v[54:57]
	v_mfma_f32_16x16x32_bf16 v[50:53], v[160:163], v[192:195], v[50:53]
	v_mfma_f32_16x16x32_bf16 v[38:41], v[152:155], v[204:207], v[38:41]
	v_mfma_f32_16x16x32_bf16 v[34:37], v[160:163], v[204:207], v[34:37]
	v_mfma_f32_16x16x32_bf16 v[22:25], v[152:155], v[212:215], v[22:25]
	v_mfma_f32_16x16x32_bf16 v[18:21], v[160:163], v[212:215], v[18:21]
	v_mfma_f32_16x16x32_bf16 v[62:65], v[156:159], v[188:191], v[62:65]
	v_mfma_f32_16x16x32_bf16 v[58:61], v[164:167], v[188:191], v[58:61]
	v_mfma_f32_16x16x32_bf16 v[54:57], v[156:159], v[200:203], v[54:57]
	v_mfma_f32_16x16x32_bf16 v[50:53], v[164:167], v[200:203], v[50:53]
	v_mfma_f32_16x16x32_bf16 v[38:41], v[156:159], v[208:211], v[38:41]
	v_mfma_f32_16x16x32_bf16 v[34:37], v[164:167], v[208:211], v[34:37]
	v_mfma_f32_16x16x32_bf16 v[22:25], v[156:159], v[216:219], v[22:25]
	v_mfma_f32_16x16x32_bf16 v[18:21], v[164:167], v[216:219], v[18:21]
	v_mfma_f32_16x16x32_bf16 v[46:49], v[168:171], v[184:187], v[46:49]
	v_mfma_f32_16x16x32_bf16 v[42:45], v[176:179], v[184:187], v[42:45]
	v_mfma_f32_16x16x32_bf16 v[30:33], v[168:171], v[192:195], v[30:33]
	v_mfma_f32_16x16x32_bf16 v[26:29], v[176:179], v[192:195], v[26:29]
	v_mfma_f32_16x16x32_bf16 v[14:17], v[168:171], v[204:207], v[14:17]
	v_mfma_f32_16x16x32_bf16 v[10:13], v[176:179], v[204:207], v[10:13]
	v_mfma_f32_16x16x32_bf16 v[6:9], v[168:171], v[212:215], v[6:9]
	v_mfma_f32_16x16x32_bf16 v[2:5], v[176:179], v[212:215], v[2:5]
	v_mfma_f32_16x16x32_bf16 v[46:49], v[172:175], v[188:191], v[46:49]
	v_mfma_f32_16x16x32_bf16 v[42:45], v[180:183], v[188:191], v[42:45]
	v_mfma_f32_16x16x32_bf16 v[30:33], v[172:175], v[200:203], v[30:33]
	v_mfma_f32_16x16x32_bf16 v[26:29], v[180:183], v[200:203], v[26:29]
	v_mfma_f32_16x16x32_bf16 v[14:17], v[172:175], v[208:211], v[14:17]
	v_mfma_f32_16x16x32_bf16 v[10:13], v[180:183], v[208:211], v[10:13]
	v_mfma_f32_16x16x32_bf16 v[6:9], v[172:175], v[216:219], v[6:9]
	v_mfma_f32_16x16x32_bf16 v[2:5], v[180:183], v[216:219], v[2:5]
	s_setprio 0
	s_barrier
	s_add_i32 s82, 0, 0x18000
	s_add_i32 s83, 0, 0x1c000
	v_add_u32_e32 v164, s82, v147
	v_add_u32_e32 v180, s83, v147
	ds_read_b128 v[152:155], v164
	ds_read_b128 v[156:159], v164 offset:1024
	ds_read_b128 v[160:163], v164 offset:2048
	ds_read_b128 v[164:167], v164 offset:3072
	ds_read_b128 v[168:171], v180
	ds_read_b128 v[172:175], v180 offset:1024
	ds_read_b128 v[176:179], v180 offset:2048
	ds_read_b128 v[180:183], v180 offset:3072
	s_add_u32 s54, s54, 0x80000
	s_addc_u32 s55, s55, 0
	s_mov_b32 m0, s53
	v_lshl_add_u64 v[226:227], s[54:55], 0, v[130:131]
	ds_read_b128 v[184:187], v151 offset:32768
	ds_read_b128 v[188:191], v151 offset:33792
	ds_read_b128 v[192:195], v151 offset:34816
	ds_read_b128 v[200:203], v151 offset:35840
	ds_read_b128 v[204:207], v151 offset:36864
	ds_read_b128 v[208:211], v151 offset:37888
	ds_read_b128 v[212:215], v151 offset:38912
	ds_read_b128 v[216:219], v151 offset:39936
	global_load_lds_dwordx4 v[226:227], off
	v_lshl_add_u64 v[226:227], s[54:55], 0, v[134:135]
	s_mov_b32 m0, s56
	s_nop 0
	global_load_lds_dwordx4 v[226:227], off
	s_waitcnt vmcnt(8)
	s_waitcnt lgkmcnt(0)
	s_barrier
	s_setprio 1
	s_waitcnt lgkmcnt(0)
	v_mfma_f32_16x16x32_bf16 v[126:129], v[152:155], v[184:187], v[126:129]
	v_mfma_f32_16x16x32_bf16 v[122:125], v[160:163], v[184:187], v[122:125]
	v_mfma_f32_16x16x32_bf16 v[118:121], v[152:155], v[192:195], v[118:121]
	v_mfma_f32_16x16x32_bf16 v[114:117], v[160:163], v[192:195], v[114:117]
	v_mfma_f32_16x16x32_bf16 v[102:105], v[152:155], v[204:207], v[102:105]
	v_mfma_f32_16x16x32_bf16 v[98:101], v[160:163], v[204:207], v[98:101]
	v_mfma_f32_16x16x32_bf16 v[86:89], v[152:155], v[212:215], v[86:89]
	v_mfma_f32_16x16x32_bf16 v[82:85], v[160:163], v[212:215], v[82:85]
	v_mfma_f32_16x16x32_bf16 v[126:129], v[156:159], v[188:191], v[126:129]
	v_mfma_f32_16x16x32_bf16 v[122:125], v[164:167], v[188:191], v[122:125]
	v_mfma_f32_16x16x32_bf16 v[118:121], v[156:159], v[200:203], v[118:121]
	v_mfma_f32_16x16x32_bf16 v[114:117], v[164:167], v[200:203], v[114:117]
	v_mfma_f32_16x16x32_bf16 v[102:105], v[156:159], v[208:211], v[102:105]
	v_mfma_f32_16x16x32_bf16 v[98:101], v[164:167], v[208:211], v[98:101]
	v_mfma_f32_16x16x32_bf16 v[86:89], v[156:159], v[216:219], v[86:89]
	v_mfma_f32_16x16x32_bf16 v[82:85], v[164:167], v[216:219], v[82:85]
	v_mfma_f32_16x16x32_bf16 v[110:113], v[168:171], v[184:187], v[110:113]
	v_mfma_f32_16x16x32_bf16 v[106:109], v[176:179], v[184:187], v[106:109]
	v_mfma_f32_16x16x32_bf16 v[94:97], v[168:171], v[192:195], v[94:97]
	v_mfma_f32_16x16x32_bf16 v[90:93], v[176:179], v[192:195], v[90:93]
	v_mfma_f32_16x16x32_bf16 v[78:81], v[168:171], v[204:207], v[78:81]
	v_mfma_f32_16x16x32_bf16 v[74:77], v[176:179], v[204:207], v[74:77]
	v_mfma_f32_16x16x32_bf16 v[70:73], v[168:171], v[212:215], v[70:73]
	v_mfma_f32_16x16x32_bf16 v[66:69], v[176:179], v[212:215], v[66:69]
	v_mfma_f32_16x16x32_bf16 v[110:113], v[172:175], v[188:191], v[110:113]
	v_mfma_f32_16x16x32_bf16 v[106:109], v[180:183], v[188:191], v[106:109]
	v_mfma_f32_16x16x32_bf16 v[94:97], v[172:175], v[200:203], v[94:97]
	v_mfma_f32_16x16x32_bf16 v[90:93], v[180:183], v[200:203], v[90:93]
	v_mfma_f32_16x16x32_bf16 v[78:81], v[172:175], v[208:211], v[78:81]
	v_mfma_f32_16x16x32_bf16 v[74:77], v[180:183], v[208:211], v[74:77]
	v_mfma_f32_16x16x32_bf16 v[70:73], v[172:175], v[216:219], v[70:73]
	v_mfma_f32_16x16x32_bf16 v[66:69], v[180:183], v[216:219], v[66:69]
	s_setprio 0
	s_barrier
; #define PG8_STAGE(bufoff, gbase, voff) do { _Pragma("unroll") for (int _i = 0; _i < 2; ++_i) \
;         __builtin_amdgcn_global_load_lds((const unsigned*)((const char*)(gbase) + (voff)[_i]), (PG8_LAS unsigned*)(lds + (bufoff) + ldsw + _i * 8192), 16, 0, 0); } while (0)
; #define PG8_LDA(dst, b, h) do { _Pragma("unroll") for (int m = 0; m < 4; ++m) _Pragma("unroll") for (int k = 0; k < 2; ++k) dst[m][k] = *(const PG8_LAS bf16x8*)(lds + PG8_SA(b, h) + aoff + m * 2048 + k * 1024); } while (0)
; #define PG8_MMA(ai, bj, At, Bt) do { __builtin_amdgcn_s_setprio(1); _Pragma("unroll") for (int m = 0; m < 4; ++m) _Pragma("unroll") for (int n = 0; n < 2; ++n) _Pragma("unroll") for (int k = 0; k < 2; ++k) \
;         acc[ai][bj][m][n] = __builtin_amdgcn_mfma_f32_16x16x32_bf16(Bt[n][k], At[m][k], acc[ai][bj][m][n], 0, 0, 0); __builtin_amdgcn_s_setprio(0); } while (0)
; #define PG8_WAIT_V(n) asm volatile("s_waitcnt vmcnt(" #n ")" ::: "memory")
; #define PG8_WAIT_L(n) asm volatile("s_waitcnt lgkmcnt(" #n ")" ::: "memory")
; #define PG8_BAR __builtin_amdgcn_s_barrier()
; #define PG8_SCHED __builtin_amdgcn_sched_barrier(0)
; template <class Epi, class Sched, bool ALIGN_EPI = false, bool SP2 = false, bool MID = false>
; __device__ __forceinline__ void gemm_phase(PG8_LAS unsigned char* lds, const Gemm g, const Sched& S, const Epi& E) {
;     ...
;         for (int t = 0; t < nt; t += 2) {
;             const bool last = (t == nt - 2);
;             if constexpr (MID) { if (t == Epi::MID_T) { PG8_SCHED; E.mid(acc, cur, wr, wc, fr, fq); PG8_SCHED; } }
;             const char* a1 = cA + (size_t)(t + 1) * kstep;
;             const char* a2 = last ? nA : cA + (size_t)(t + 2) * kstep; const char* b2 = last ? nB : cB + (size_t)(t + 2) * kstep;
;             const char* a3 = a2 + kstep; const char* b3 = b2 + kstep;
;             if (last && has_next) S.a_ready(nxt);
;     ...
;             PG8_LDA(At, 1, 1); PG8_STAGE(PG8_SB(1, 0), b3, voffB); PG8_STAGE(PG8_SB(1, 1), b3 + hstep, voffB); PG8_STAGE(PG8_SA(1, 0), a3, voffA);
;             PG8_WAIT_V(8); PG8_WAIT_L(0); PG8_BAR; PG8_MMA(1, 0, At, B0); PG8_MMA(1, 1, At, B1); PG8_BAR; PG8_SCHED;
	s_add_i32 s54, s82, s15
	v_lshl_add_u64 v[196:197], v[196:197], 0, s[18:19]
	s_mov_b32 m0, s54
	ds_read_b128 v[184:187], v151 offset:49152
	ds_read_b128 v[188:191], v151 offset:50176
	ds_read_b128 v[192:195], v151 offset:51200
	ds_read_b128 v[200:203], v151 offset:52224
	ds_read_b128 v[204:207], v151 offset:53248
	ds_read_b128 v[208:211], v151 offset:54272
	ds_read_b128 v[212:215], v151 offset:55296
	ds_read_b128 v[216:219], v151 offset:56320
	global_load_lds_dwordx4 v[196:197], off
	s_add_i32 m0, s54, 0x2000
	s_add_u32 s50, s50, 0x80080
	v_lshl_add_u64 v[196:197], v[220:221], 0, s[18:19]
	s_addc_u32 s51, s51, 0
	s_add_i32 s54, s83, s15
	global_load_lds_dwordx4 v[196:197], off
	v_lshl_add_u64 v[196:197], s[50:51], 0, v[132:133]
	s_mov_b32 m0, s54
	s_nop 0
	global_load_lds_dwordx4 v[196:197], off
	v_lshl_add_u64 v[196:197], s[50:51], 0, v[136:137]
	s_add_i32 m0, s54, 0x2000
	s_nop 0
	global_load_lds_dwordx4 v[196:197], off
	v_lshl_add_u64 v[196:197], v[222:223], 0, s[18:19]
	s_mov_b32 m0, s58
	s_nop 0
	global_load_lds_dwordx4 v[196:197], off
	v_lshl_add_u64 v[196:197], v[224:225], 0, s[18:19]
	s_mov_b32 m0, s59
	s_nop 0
	global_load_lds_dwordx4 v[196:197], off
	s_waitcnt vmcnt(8)
	s_waitcnt lgkmcnt(0)
	s_barrier
	s_setprio 1
	s_waitcnt lgkmcnt(0)
	v_mfma_f32_16x16x32_bf16 v[62:65], v[152:155], v[184:187], v[62:65]
	v_mfma_f32_16x16x32_bf16 v[58:61], v[160:163], v[184:187], v[58:61]
	v_mfma_f32_16x16x32_bf16 v[54:57], v[152:155], v[192:195], v[54:57]
	v_mfma_f32_16x16x32_bf16 v[50:53], v[160:163], v[192:195], v[50:53]
	v_mfma_f32_16x16x32_bf16 v[38:41], v[152:155], v[204:207], v[38:41]
	v_mfma_f32_16x16x32_bf16 v[34:37], v[160:163], v[204:207], v[34:37]
	v_mfma_f32_16x16x32_bf16 v[22:25], v[152:155], v[212:215], v[22:25]
	v_mfma_f32_16x16x32_bf16 v[18:21], v[160:163], v[212:215], v[18:21]
	v_mfma_f32_16x16x32_bf16 v[62:65], v[156:159], v[188:191], v[62:65]
	v_mfma_f32_16x16x32_bf16 v[58:61], v[164:167], v[188:191], v[58:61]
	v_mfma_f32_16x16x32_bf16 v[54:57], v[156:159], v[200:203], v[54:57]
	v_mfma_f32_16x16x32_bf16 v[50:53], v[164:167], v[200:203], v[50:53]
	v_mfma_f32_16x16x32_bf16 v[38:41], v[156:159], v[208:211], v[38:41]
	v_mfma_f32_16x16x32_bf16 v[34:37], v[164:167], v[208:211], v[34:37]
	v_mfma_f32_16x16x32_bf16 v[22:25], v[156:159], v[216:219], v[22:25]
	v_mfma_f32_16x16x32_bf16 v[18:21], v[164:167], v[216:219], v[18:21]
	v_mfma_f32_16x16x32_bf16 v[46:49], v[168:171], v[184:187], v[46:49]
	v_mfma_f32_16x16x32_bf16 v[42:45], v[176:179], v[184:187], v[42:45]
	v_mfma_f32_16x16x32_bf16 v[30:33], v[168:171], v[192:195], v[30:33]
	v_mfma_f32_16x16x32_bf16 v[26:29], v[176:179], v[192:195], v[26:29]
	v_mfma_f32_16x16x32_bf16 v[14:17], v[168:171], v[204:207], v[14:17]
	v_mfma_f32_16x16x32_bf16 v[10:13], v[176:179], v[204:207], v[10:13]
	v_mfma_f32_16x16x32_bf16 v[6:9], v[168:171], v[212:215], v[6:9]
	v_mfma_f32_16x16x32_bf16 v[2:5], v[176:179], v[212:215], v[2:5]
	v_mfma_f32_16x16x32_bf16 v[46:49], v[172:175], v[188:191], v[46:49]
	v_mfma_f32_16x16x32_bf16 v[42:45], v[180:183], v[188:191], v[42:45]
	v_mfma_f32_16x16x32_bf16 v[30:33], v[172:175], v[200:203], v[30:33]
	v_mfma_f32_16x16x32_bf16 v[26:29], v[180:183], v[200:203], v[26:29]
	v_mfma_f32_16x16x32_bf16 v[14:17], v[172:175], v[208:211], v[14:17]
	v_mfma_f32_16x16x32_bf16 v[10:13], v[180:183], v[208:211], v[10:13]
	v_mfma_f32_16x16x32_bf16 v[6:9], v[172:175], v[216:219], v[6:9]
	v_mfma_f32_16x16x32_bf16 v[2:5], v[180:183], v[216:219], v[2:5]
	s_setprio 0
	s_barrier
	s_add_i32 s81, s81, 2
	s_add_u32 s48, s48, 0x100
	s_addc_u32 s49, s49, 0
	s_add_u32 s79, s79, 0x100
	s_addc_u32 s80, s80, 0
	s_cmp_gt_u32 s81, 29
	s_cbranch_scc0 .LBB0_1528
	s_and_b64 vcc, exec, s[20:21]
	s_cbranch_vccz .LBB0_1531
	s_barrier

; #define PG8_STAGE(bufoff, gbase, voff) do { _Pragma("unroll") for (int _i = 0; _i < 2; ++_i) \
;         __builtin_amdgcn_global_load_lds((const unsigned*)((const char*)(gbase) + (voff)[_i]), (PG8_LAS unsigned*)(lds + (bufoff) + ldsw + _i * 8192), 16, 0, 0); } while (0)
; #define PG8_LDA(dst, b, h) do { _Pragma("unroll") for (int m = 0; m < 4; ++m) _Pragma("unroll") for (int k = 0; k < 2; ++k) dst[m][k] = *(const PG8_LAS bf16x8*)(lds + PG8_SA(b, h) + aoff + m * 2048 + k * 1024); } while (0)
; #define PG8_LDB(dst, b, h) do { _Pragma("unroll") for (int n = 0; n < 2; ++n) _Pragma("unroll") for (int k = 0; k < 2; ++k) dst[n][k] = *(const PG8_LAS bf16x8*)(lds + PG8_SB(b, h) + boff + n * 2048 + k * 1024); } while (0)
; #define PG8_MMA(ai, bj, At, Bt) do { __builtin_amdgcn_s_setprio(1); _Pragma("unroll") for (int m = 0; m < 4; ++m) _Pragma("unroll") for (int n = 0; n < 2; ++n) _Pragma("unroll") for (int k = 0; k < 2; ++k) \
;         acc[ai][bj][m][n] = __builtin_amdgcn_mfma_f32_16x16x32_bf16(Bt[n][k], At[m][k], acc[ai][bj][m][n], 0, 0, 0); __builtin_amdgcn_s_setprio(0); } while (0)
; #define PG8_WAIT_V(n) asm volatile("s_waitcnt vmcnt(" #n ")" ::: "memory")
; #define PG8_WAIT_L(n) asm volatile("s_waitcnt lgkmcnt(" #n ")" ::: "memory")
; #define PG8_BAR __builtin_amdgcn_s_barrier()
; #define PG8_SCHED __builtin_amdgcn_sched_barrier(0)
; template <class Epi, class Sched, bool ALIGN_EPI = false, bool SP2 = false, bool MID = false>
; __device__ __forceinline__ void gemm_phase(PG8_LAS unsigned char* lds, const Gemm g, const Sched& S, const Epi& E) {
;     ...
;             PG8_LDB(B0, 0, 0); PG8_LDB(B1, 0, 1); PG8_SCHED; PG8_LDA(At, 0, 0); PG8_STAGE(PG8_SA(1, 1), a1 + hstep, voffA);
;             PG8_WAIT_V(8); PG8_WAIT_L(0); PG8_BAR; PG8_MMA(0, 0, At, B0); PG8_MMA(0, 1, At, B1); PG8_BAR; PG8_SCHED;
;             PG8_LDA(At, 0, 1); PG8_STAGE(PG8_SB(0, 0), b2, voffB); PG8_STAGE(PG8_SB(0, 1), b2 + hstep, voffB); PG8_STAGE(PG8_SA(0, 0), a2, voffA);
;             PG8_WAIT_V(8); PG8_WAIT_L(0); PG8_BAR; PG8_MMA(1, 0, At, B0); PG8_MMA(1, 1, At, B1); PG8_BAR; PG8_SCHED;
.LBB0_1685:
	ds_read_b128 v[146:149], v157
	ds_read_b128 v[150:153], v157 offset:1024
	ds_read_b128 v[160:163], v157 offset:2048
	ds_read_b128 v[164:167], v157 offset:3072
	ds_read_b128 v[168:171], v158
	ds_read_b128 v[172:175], v158 offset:1024
	ds_read_b128 v[176:179], v158 offset:2048
	ds_read_b128 v[180:183], v158 offset:3072
	s_add_u32 s48, s46, 0xfff80080
	s_addc_u32 s49, s47, -1
	s_cmp_eq_u32 s79, 28
	s_cselect_b32 s51, s39, s49
	s_cselect_b32 s50, s75, s48
	s_cselect_b32 s49, s37, s78
	s_cselect_b32 s48, s76, s77
	v_lshl_add_u64 v[196:197], s[46:47], 0, v[138:139]
	s_add_i32 m0, s45, 0xc000
	ds_read_b128 v[184:187], v159
	ds_read_b128 v[188:191], v159 offset:1024
	ds_read_b128 v[192:195], v159 offset:2048
	ds_read_b128 v[200:203], v159 offset:3072
	ds_read_b128 v[204:207], v159 offset:4096
	ds_read_b128 v[208:211], v159 offset:5120
	ds_read_b128 v[212:215], v159 offset:6144
	ds_read_b128 v[216:219], v159 offset:7168
	global_load_lds_dwordx4 v[196:197], off
	v_lshl_add_u64 v[196:197], s[46:47], 0, v[140:141]
	s_add_i32 m0, s45, 0xe000
	s_nop 0
	global_load_lds_dwordx4 v[196:197], off
	s_waitcnt vmcnt(8)
	s_waitcnt lgkmcnt(0)
	s_barrier
	s_setprio 1
	s_waitcnt lgkmcnt(0)
	v_mfma_f32_16x16x32_bf16 v[126:129], v[146:149], v[184:187], v[126:129]
	v_mfma_f32_16x16x32_bf16 v[122:125], v[160:163], v[184:187], v[122:125]
	v_mfma_f32_16x16x32_bf16 v[110:113], v[146:149], v[192:195], v[110:113]
	v_mfma_f32_16x16x32_bf16 v[106:109], v[160:163], v[192:195], v[106:109]
	v_mfma_f32_16x16x32_bf16 v[94:97], v[146:149], v[204:207], v[94:97]
	v_mfma_f32_16x16x32_bf16 v[90:93], v[160:163], v[204:207], v[90:93]
	v_mfma_f32_16x16x32_bf16 v[78:81], v[146:149], v[212:215], v[78:81]
	v_mfma_f32_16x16x32_bf16 v[74:77], v[160:163], v[212:215], v[74:77]
	v_mfma_f32_16x16x32_bf16 v[126:129], v[150:153], v[188:191], v[126:129]
	v_mfma_f32_16x16x32_bf16 v[122:125], v[164:167], v[188:191], v[122:125]
	v_mfma_f32_16x16x32_bf16 v[110:113], v[150:153], v[200:203], v[110:113]
	v_mfma_f32_16x16x32_bf16 v[106:109], v[164:167], v[200:203], v[106:109]
	v_mfma_f32_16x16x32_bf16 v[94:97], v[150:153], v[208:211], v[94:97]
	v_mfma_f32_16x16x32_bf16 v[90:93], v[164:167], v[208:211], v[90:93]
	v_mfma_f32_16x16x32_bf16 v[78:81], v[150:153], v[216:219], v[78:81]
	v_mfma_f32_16x16x32_bf16 v[74:77], v[164:167], v[216:219], v[74:77]
	v_mfma_f32_16x16x32_bf16 v[118:121], v[168:171], v[184:187], v[118:121]
	v_mfma_f32_16x16x32_bf16 v[114:117], v[176:179], v[184:187], v[114:117]
	v_mfma_f32_16x16x32_bf16 v[102:105], v[168:171], v[192:195], v[102:105]
	v_mfma_f32_16x16x32_bf16 v[98:101], v[176:179], v[192:195], v[98:101]
	v_mfma_f32_16x16x32_bf16 v[86:89], v[168:171], v[204:207], v[86:89]
	v_mfma_f32_16x16x32_bf16 v[82:85], v[176:179], v[204:207], v[82:85]
	v_mfma_f32_16x16x32_bf16 v[70:73], v[168:171], v[212:215], v[70:73]
	v_mfma_f32_16x16x32_bf16 v[66:69], v[176:179], v[212:215], v[66:69]
	v_mfma_f32_16x16x32_bf16 v[118:121], v[172:175], v[188:191], v[118:121]
	v_mfma_f32_16x16x32_bf16 v[114:117], v[180:183], v[188:191], v[114:117]
	v_mfma_f32_16x16x32_bf16 v[102:105], v[172:175], v[200:203], v[102:105]
	v_mfma_f32_16x16x32_bf16 v[98:101], v[180:183], v[200:203], v[98:101]
	v_mfma_f32_16x16x32_bf16 v[86:89], v[172:175], v[208:211], v[86:89]
	v_mfma_f32_16x16x32_bf16 v[82:85], v[180:183], v[208:211], v[82:85]
	v_mfma_f32_16x16x32_bf16 v[70:73], v[172:175], v[216:219], v[70:73]
	v_mfma_f32_16x16x32_bf16 v[66:69], v[180:183], v[216:219], v[66:69]
	s_setprio 0
	s_barrier
	s_add_i32 s80, s59, s15
	v_lshl_add_u64 v[196:197], s[48:49], 0, v[132:133]
	s_mov_b32 m0, s80
	ds_read_b128 v[184:187], v159 offset:16384
	ds_read_b128 v[188:191], v159 offset:17408
	ds_read_b128 v[192:195], v159 offset:18432
	ds_read_b128 v[200:203], v159 offset:19456
	ds_read_b128 v[204:207], v159 offset:20480
	ds_read_b128 v[208:211], v159 offset:21504
	ds_read_b128 v[212:215], v159 offset:22528
	ds_read_b128 v[216:219], v159 offset:23552
	global_load_lds_dwordx4 v[196:197], off
	s_add_i32 m0, s80, 0x2000
	s_add_u32 s80, s48, 0x80000
	v_lshl_add_u64 v[220:221], s[48:49], 0, v[136:137]
	s_addc_u32 s81, s49, 0
	s_add_i32 s82, s62, s15
	global_load_lds_dwordx4 v[220:221], off
	v_lshl_add_u64 v[222:223], s[80:81], 0, v[132:133]
	s_mov_b32 m0, s82
	v_lshl_add_u64 v[224:225], s[50:51], 0, v[134:135]
	global_load_lds_dwordx4 v[222:223], off
	v_lshl_add_u64 v[222:223], s[80:81], 0, v[136:137]
	s_add_i32 m0, s82, 0x2000
	s_nop 0
	global_load_lds_dwordx4 v[222:223], off
	v_lshl_add_u64 v[222:223], s[50:51], 0, v[130:131]
	s_mov_b32 m0, s45
	s_nop 0
	global_load_lds_dwordx4 v[222:223], off
	s_mov_b32 m0, s52
	s_nop 0
	global_load_lds_dwordx4 v[224:225], off
	s_waitcnt vmcnt(8)
	s_waitcnt lgkmcnt(0)
	s_barrier
; #define PG8_STAGE(bufoff, gbase, voff) do { _Pragma("unroll") for (int _i = 0; _i < 2; ++_i) \
;         __builtin_amdgcn_global_load_lds((const unsigned*)((const char*)(gbase) + (voff)[_i]), (PG8_LAS unsigned*)(lds + (bufoff) + ldsw + _i * 8192), 16, 0, 0); } while (0)
; #define PG8_LDA(dst, b, h) do { _Pragma("unroll") for (int m = 0; m < 4; ++m) _Pragma("unroll") for (int k = 0; k < 2; ++k) dst[m][k] = *(const PG8_LAS bf16x8*)(lds + PG8_SA(b, h) + aoff + m * 2048 + k * 1024); } while (0)
; #define PG8_LDB(dst, b, h) do { _Pragma("unroll") for (int n = 0; n < 2; ++n) _Pragma("unroll") for (int k = 0; k < 2; ++k) dst[n][k] = *(const PG8_LAS bf16x8*)(lds + PG8_SB(b, h) + boff + n * 2048 + k * 1024); } while (0)
; #define PG8_MMA(ai, bj, At, Bt) do { __builtin_amdgcn_s_setprio(1); _Pragma("unroll") for (int m = 0; m < 4; ++m) _Pragma("unroll") for (int n = 0; n < 2; ++n) _Pragma("unroll") for (int k = 0; k < 2; ++k) \
;         acc[ai][bj][m][n] = __builtin_amdgcn_mfma_f32_16x16x32_bf16(Bt[n][k], At[m][k], acc[ai][bj][m][n], 0, 0, 0); __builtin_amdgcn_s_setprio(0); } while (0)
; #define PG8_WAIT_V(n) asm volatile("s_waitcnt vmcnt(" #n ")" ::: "memory")
; #define PG8_WAIT_L(n) asm volatile("s_waitcnt lgkmcnt(" #n ")" ::: "memory")
; #define PG8_BAR __builtin_amdgcn_s_barrier()
; #define PG8_SCHED __builtin_amdgcn_sched_barrier(0)
; template <class Epi, class Sched, bool ALIGN_EPI = false, bool SP2 = false, bool MID = false>
; __device__ __forceinline__ void gemm_phase(PG8_LAS unsigned char* lds, const Gemm g, const Sched& S, const Epi& E) {
;     ...
;             PG8_WAIT_V(8); PG8_WAIT_L(0); PG8_BAR; PG8_MMA(1, 0, At, B0); PG8_MMA(1, 1, At, B1); PG8_BAR; PG8_SCHED;
;             PG8_LDB(B0, 1, 0); PG8_LDB(B1, 1, 1); PG8_SCHED; PG8_LDA(At, 1, 0); PG8_STAGE(PG8_SA(0, 1), a2 + hstep, voffA);
;             PG8_WAIT_V(8); PG8_WAIT_L(0); PG8_BAR; PG8_MMA(0, 0, At, B0); PG8_MMA(0, 1, At, B1); PG8_BAR; PG8_SCHED;
	s_setprio 1
	s_waitcnt lgkmcnt(0)
	v_mfma_f32_16x16x32_bf16 v[62:65], v[146:149], v[184:187], v[62:65]
	v_mfma_f32_16x16x32_bf16 v[58:61], v[160:163], v[184:187], v[58:61]
	v_mfma_f32_16x16x32_bf16 v[46:49], v[146:149], v[192:195], v[46:49]
	v_mfma_f32_16x16x32_bf16 v[42:45], v[160:163], v[192:195], v[42:45]
	v_mfma_f32_16x16x32_bf16 v[30:33], v[146:149], v[204:207], v[30:33]
	v_mfma_f32_16x16x32_bf16 v[26:29], v[160:163], v[204:207], v[26:29]
	v_mfma_f32_16x16x32_bf16 v[14:17], v[146:149], v[212:215], v[14:17]
	v_mfma_f32_16x16x32_bf16 v[10:13], v[160:163], v[212:215], v[10:13]
	v_mfma_f32_16x16x32_bf16 v[62:65], v[150:153], v[188:191], v[62:65]
	v_mfma_f32_16x16x32_bf16 v[58:61], v[164:167], v[188:191], v[58:61]
	v_mfma_f32_16x16x32_bf16 v[46:49], v[150:153], v[200:203], v[46:49]
	v_mfma_f32_16x16x32_bf16 v[42:45], v[164:167], v[200:203], v[42:45]
	v_mfma_f32_16x16x32_bf16 v[30:33], v[150:153], v[208:211], v[30:33]
	v_mfma_f32_16x16x32_bf16 v[26:29], v[164:167], v[208:211], v[26:29]
	v_mfma_f32_16x16x32_bf16 v[14:17], v[150:153], v[216:219], v[14:17]
	v_mfma_f32_16x16x32_bf16 v[10:13], v[164:167], v[216:219], v[10:13]
	v_mfma_f32_16x16x32_bf16 v[54:57], v[168:171], v[184:187], v[54:57]
	v_mfma_f32_16x16x32_bf16 v[50:53], v[176:179], v[184:187], v[50:53]
	v_mfma_f32_16x16x32_bf16 v[38:41], v[168:171], v[192:195], v[38:41]
	v_mfma_f32_16x16x32_bf16 v[34:37], v[176:179], v[192:195], v[34:37]
	v_mfma_f32_16x16x32_bf16 v[22:25], v[168:171], v[204:207], v[22:25]
	v_mfma_f32_16x16x32_bf16 v[18:21], v[176:179], v[204:207], v[18:21]
	v_mfma_f32_16x16x32_bf16 v[6:9], v[168:171], v[212:215], v[6:9]
	v_mfma_f32_16x16x32_bf16 v[2:5], v[176:179], v[212:215], v[2:5]
	v_mfma_f32_16x16x32_bf16 v[54:57], v[172:175], v[188:191], v[54:57]
	v_mfma_f32_16x16x32_bf16 v[50:53], v[180:183], v[188:191], v[50:53]
	v_mfma_f32_16x16x32_bf16 v[38:41], v[172:175], v[200:203], v[38:41]
	v_mfma_f32_16x16x32_bf16 v[34:37], v[180:183], v[200:203], v[34:37]
	v_mfma_f32_16x16x32_bf16 v[22:25], v[172:175], v[208:211], v[22:25]
	v_mfma_f32_16x16x32_bf16 v[18:21], v[180:183], v[208:211], v[18:21]
	v_mfma_f32_16x16x32_bf16 v[6:9], v[172:175], v[216:219], v[6:9]
	v_mfma_f32_16x16x32_bf16 v[2:5], v[180:183], v[216:219], v[2:5]
	s_setprio 0
	s_barrier
	s_add_i32 s80, 0, 0x18000
	s_add_i32 s81, 0, 0x1c000
	v_add_u32_e32 v164, s80, v155
	v_add_u32_e32 v180, s81, v155
	ds_read_b128 v[146:149], v164
	ds_read_b128 v[150:153], v164 offset:1024
	ds_read_b128 v[160:163], v164 offset:2048
	ds_read_b128 v[164:167], v164 offset:3072
	ds_read_b128 v[168:171], v180
	ds_read_b128 v[172:175], v180 offset:1024
	ds_read_b128 v[176:179], v180 offset:2048
	ds_read_b128 v[180:183], v180 offset:3072
	s_add_u32 s50, s50, 0x80000
	s_addc_u32 s51, s51, 0
	s_mov_b32 m0, s53
	v_lshl_add_u64 v[226:227], s[50:51], 0, v[130:131]
	ds_read_b128 v[184:187], v159 offset:32768
	ds_read_b128 v[188:191], v159 offset:33792
	ds_read_b128 v[192:195], v159 offset:34816
	ds_read_b128 v[200:203], v159 offset:35840
	ds_read_b128 v[204:207], v159 offset:36864
	ds_read_b128 v[208:211], v159 offset:37888
	ds_read_b128 v[212:215], v159 offset:38912
	ds_read_b128 v[216:219], v159 offset:39936
	global_load_lds_dwordx4 v[226:227], off
	v_lshl_add_u64 v[226:227], s[50:51], 0, v[134:135]
	s_mov_b32 m0, s54
	s_nop 0
	global_load_lds_dwordx4 v[226:227], off
	s_waitcnt vmcnt(8)
	s_waitcnt lgkmcnt(0)
	s_barrier
	s_setprio 1
	s_waitcnt lgkmcnt(0)
	v_mfma_f32_16x16x32_bf16 v[126:129], v[146:149], v[184:187], v[126:129]
	v_mfma_f32_16x16x32_bf16 v[122:125], v[160:163], v[184:187], v[122:125]
	v_mfma_f32_16x16x32_bf16 v[110:113], v[146:149], v[192:195], v[110:113]
	v_mfma_f32_16x16x32_bf16 v[106:109], v[160:163], v[192:195], v[106:109]
	v_mfma_f32_16x16x32_bf16 v[94:97], v[146:149], v[204:207], v[94:97]
	v_mfma_f32_16x16x32_bf16 v[90:93], v[160:163], v[204:207], v[90:93]
	v_mfma_f32_16x16x32_bf16 v[78:81], v[146:149], v[212:215], v[78:81]
	v_mfma_f32_16x16x32_bf16 v[74:77], v[160:163], v[212:215], v[74:77]
	v_mfma_f32_16x16x32_bf16 v[126:129], v[150:153], v[188:191], v[126:129]
	v_mfma_f32_16x16x32_bf16 v[122:125], v[164:167], v[188:191], v[122:125]
	v_mfma_f32_16x16x32_bf16 v[110:113], v[150:153], v[200:203], v[110:113]
	v_mfma_f32_16x16x32_bf16 v[106:109], v[164:167], v[200:203], v[106:109]
	v_mfma_f32_16x16x32_bf16 v[94:97], v[150:153], v[208:211], v[94:97]
	v_mfma_f32_16x16x32_bf16 v[90:93], v[164:167], v[208:211], v[90:93]
	v_mfma_f32_16x16x32_bf16 v[78:81], v[150:153], v[216:219], v[78:81]
	v_mfma_f32_16x16x32_bf16 v[74:77], v[164:167], v[216:219], v[74:77]
	v_mfma_f32_16x16x32_bf16 v[118:121], v[168:171], v[184:187], v[118:121]
	v_mfma_f32_16x16x32_bf16 v[114:117], v[176:179], v[184:187], v[114:117]
	v_mfma_f32_16x16x32_bf16 v[102:105], v[168:171], v[192:195], v[102:105]
	v_mfma_f32_16x16x32_bf16 v[98:101], v[176:179], v[192:195], v[98:101]
	v_mfma_f32_16x16x32_bf16 v[86:89], v[168:171], v[204:207], v[86:89]
	v_mfma_f32_16x16x32_bf16 v[82:85], v[176:179], v[204:207], v[82:85]
	v_mfma_f32_16x16x32_bf16 v[70:73], v[168:171], v[212:215], v[70:73]
	v_mfma_f32_16x16x32_bf16 v[66:69], v[176:179], v[212:215], v[66:69]
	v_mfma_f32_16x16x32_bf16 v[118:121], v[172:175], v[188:191], v[118:121]
	v_mfma_f32_16x16x32_bf16 v[114:117], v[180:183], v[188:191], v[114:117]
	v_mfma_f32_16x16x32_bf16 v[102:105], v[172:175], v[200:203], v[102:105]
	v_mfma_f32_16x16x32_bf16 v[98:101], v[180:183], v[200:203], v[98:101]
	v_mfma_f32_16x16x32_bf16 v[86:89], v[172:175], v[208:211], v[86:89]
	v_mfma_f32_16x16x32_bf16 v[82:85], v[180:183], v[208:211], v[82:85]
	v_mfma_f32_16x16x32_bf16 v[70:73], v[172:175], v[216:219], v[70:73]
	v_mfma_f32_16x16x32_bf16 v[66:69], v[180:183], v[216:219], v[66:69]
	s_setprio 0
	s_barrier
; #define PG8_STAGE(bufoff, gbase, voff) do { _Pragma("unroll") for (int _i = 0; _i < 2; ++_i) \
;         __builtin_amdgcn_global_load_lds((const unsigned*)((const char*)(gbase) + (voff)[_i]), (PG8_LAS unsigned*)(lds + (bufoff) + ldsw + _i * 8192), 16, 0, 0); } while (0)
; #define PG8_LDA(dst, b, h) do { _Pragma("unroll") for (int m = 0; m < 4; ++m) _Pragma("unroll") for (int k = 0; k < 2; ++k) dst[m][k] = *(const PG8_LAS bf16x8*)(lds + PG8_SA(b, h) + aoff + m * 2048 + k * 1024); } while (0)
; #define PG8_MMA(ai, bj, At, Bt) do { __builtin_amdgcn_s_setprio(1); _Pragma("unroll") for (int m = 0; m < 4; ++m) _Pragma("unroll") for (int n = 0; n < 2; ++n) _Pragma("unroll") for (int k = 0; k < 2; ++k) \
;         acc[ai][bj][m][n] = __builtin_amdgcn_mfma_f32_16x16x32_bf16(Bt[n][k], At[m][k], acc[ai][bj][m][n], 0, 0, 0); __builtin_amdgcn_s_setprio(0); } while (0)
; #define PG8_WAIT_V(n) asm volatile("s_waitcnt vmcnt(" #n ")" ::: "memory")
; #define PG8_WAIT_L(n) asm volatile("s_waitcnt lgkmcnt(" #n ")" ::: "memory")
; #define PG8_BAR __builtin_amdgcn_s_barrier()
; #define PG8_SCHED __builtin_amdgcn_sched_barrier(0)
; template <class Epi, class Sched, bool ALIGN_EPI = false, bool SP2 = false, bool MID = false>
; __device__ __forceinline__ void gemm_phase(PG8_LAS unsigned char* lds, const Gemm g, const Sched& S, const Epi& E) {
;     ...
;         for (int t = 0; t < nt; t += 2) {
;             const bool last = (t == nt - 2);
;             if constexpr (MID) { if (t == Epi::MID_T) { PG8_SCHED; E.mid(acc, cur, wr, wc, fr, fq); PG8_SCHED; } }
;             const char* a1 = cA + (size_t)(t + 1) * kstep;
;             const char* a2 = last ? nA : cA + (size_t)(t + 2) * kstep; const char* b2 = last ? nB : cB + (size_t)(t + 2) * kstep;
;             const char* a3 = a2 + kstep; const char* b3 = b2 + kstep;
;             if (last && has_next) S.a_ready(nxt);
;     ...
;             PG8_LDA(At, 1, 1); PG8_STAGE(PG8_SB(1, 0), b3, voffB); PG8_STAGE(PG8_SB(1, 1), b3 + hstep, voffB); PG8_STAGE(PG8_SA(1, 0), a3, voffA);
;             PG8_WAIT_V(8); PG8_WAIT_L(0); PG8_BAR; PG8_MMA(1, 0, At, B0); PG8_MMA(1, 1, At, B1); PG8_BAR; PG8_SCHED;
	s_add_i32 s50, s80, s15
	v_lshl_add_u64 v[196:197], v[196:197], 0, s[16:17]
	s_mov_b32 m0, s50
	ds_read_b128 v[184:187], v159 offset:49152
	ds_read_b128 v[188:191], v159 offset:50176
	ds_read_b128 v[192:195], v159 offset:51200
	ds_read_b128 v[200:203], v159 offset:52224
	ds_read_b128 v[204:207], v159 offset:53248
	ds_read_b128 v[208:211], v159 offset:54272
	ds_read_b128 v[212:215], v159 offset:55296
	ds_read_b128 v[216:219], v159 offset:56320
	global_load_lds_dwordx4 v[196:197], off
	s_add_i32 m0, s50, 0x2000
	s_add_u32 s48, s48, 0x80080
	v_lshl_add_u64 v[196:197], v[220:221], 0, s[16:17]
	s_addc_u32 s49, s49, 0
	s_add_i32 s50, s81, s15
	global_load_lds_dwordx4 v[196:197], off
	v_lshl_add_u64 v[196:197], s[48:49], 0, v[132:133]
	s_mov_b32 m0, s50
	s_nop 0
	global_load_lds_dwordx4 v[196:197], off
	v_lshl_add_u64 v[196:197], s[48:49], 0, v[136:137]
	s_add_i32 m0, s50, 0x2000
	s_nop 0
	global_load_lds_dwordx4 v[196:197], off
	v_lshl_add_u64 v[196:197], v[222:223], 0, s[16:17]
	s_mov_b32 m0, s56
	s_nop 0
	global_load_lds_dwordx4 v[196:197], off
	v_lshl_add_u64 v[196:197], v[224:225], 0, s[16:17]
	s_mov_b32 m0, s57
	s_nop 0
	global_load_lds_dwordx4 v[196:197], off
	s_waitcnt vmcnt(8)
	s_waitcnt lgkmcnt(0)
	s_barrier
	s_setprio 1
	s_waitcnt lgkmcnt(0)
	v_mfma_f32_16x16x32_bf16 v[62:65], v[146:149], v[184:187], v[62:65]
	v_mfma_f32_16x16x32_bf16 v[58:61], v[160:163], v[184:187], v[58:61]
	v_mfma_f32_16x16x32_bf16 v[46:49], v[146:149], v[192:195], v[46:49]
	v_mfma_f32_16x16x32_bf16 v[42:45], v[160:163], v[192:195], v[42:45]
	v_mfma_f32_16x16x32_bf16 v[30:33], v[146:149], v[204:207], v[30:33]
	v_mfma_f32_16x16x32_bf16 v[26:29], v[160:163], v[204:207], v[26:29]
	v_mfma_f32_16x16x32_bf16 v[14:17], v[146:149], v[212:215], v[14:17]
	v_mfma_f32_16x16x32_bf16 v[10:13], v[160:163], v[212:215], v[10:13]
	v_mfma_f32_16x16x32_bf16 v[62:65], v[150:153], v[188:191], v[62:65]
	v_mfma_f32_16x16x32_bf16 v[58:61], v[164:167], v[188:191], v[58:61]
	v_mfma_f32_16x16x32_bf16 v[46:49], v[150:153], v[200:203], v[46:49]
	v_mfma_f32_16x16x32_bf16 v[42:45], v[164:167], v[200:203], v[42:45]
	v_mfma_f32_16x16x32_bf16 v[30:33], v[150:153], v[208:211], v[30:33]
	v_mfma_f32_16x16x32_bf16 v[26:29], v[164:167], v[208:211], v[26:29]
	v_mfma_f32_16x16x32_bf16 v[14:17], v[150:153], v[216:219], v[14:17]
	v_mfma_f32_16x16x32_bf16 v[10:13], v[164:167], v[216:219], v[10:13]
	v_mfma_f32_16x16x32_bf16 v[54:57], v[168:171], v[184:187], v[54:57]
	v_mfma_f32_16x16x32_bf16 v[50:53], v[176:179], v[184:187], v[50:53]
	v_mfma_f32_16x16x32_bf16 v[38:41], v[168:171], v[192:195], v[38:41]
	v_mfma_f32_16x16x32_bf16 v[34:37], v[176:179], v[192:195], v[34:37]
	v_mfma_f32_16x16x32_bf16 v[22:25], v[168:171], v[204:207], v[22:25]
	v_mfma_f32_16x16x32_bf16 v[18:21], v[176:179], v[204:207], v[18:21]
	v_mfma_f32_16x16x32_bf16 v[6:9], v[168:171], v[212:215], v[6:9]
	v_mfma_f32_16x16x32_bf16 v[2:5], v[176:179], v[212:215], v[2:5]
	v_mfma_f32_16x16x32_bf16 v[54:57], v[172:175], v[188:191], v[54:57]
	v_mfma_f32_16x16x32_bf16 v[50:53], v[180:183], v[188:191], v[50:53]
	v_mfma_f32_16x16x32_bf16 v[38:41], v[172:175], v[200:203], v[38:41]
	v_mfma_f32_16x16x32_bf16 v[34:37], v[180:183], v[200:203], v[34:37]
	v_mfma_f32_16x16x32_bf16 v[22:25], v[172:175], v[208:211], v[22:25]
	v_mfma_f32_16x16x32_bf16 v[18:21], v[180:183], v[208:211], v[18:21]
	v_mfma_f32_16x16x32_bf16 v[6:9], v[172:175], v[216:219], v[6:9]
	v_mfma_f32_16x16x32_bf16 v[2:5], v[180:183], v[216:219], v[2:5]
	s_setprio 0
	s_barrier
	s_add_i32 s79, s79, 2
	s_add_u32 s46, s46, 0x100
	s_addc_u32 s47, s47, 0
	s_add_u32 s77, s77, 0x100
	s_addc_u32 s78, s78, 0
	s_cmp_gt_u32 s79, 29
	s_cbranch_scc0 .LBB0_1685
	s_and_b64 vcc, exec, s[18:19]
	s_cbranch_vccz .LBB0_1688
	s_barrier

; #define PG8_STAGE(bufoff, gbase, voff) do { _Pragma("unroll") for (int _i = 0; _i < 2; ++_i) \
;         __builtin_amdgcn_global_load_lds((const unsigned*)((const char*)(gbase) + (voff)[_i]), (PG8_LAS unsigned*)(lds + (bufoff) + ldsw + _i * 8192), 16, 0, 0); } while (0)
; #define PG8_LDA(dst, b, h) do { _Pragma("unroll") for (int m = 0; m < 4; ++m) _Pragma("unroll") for (int k = 0; k < 2; ++k) dst[m][k] = *(const PG8_LAS bf16x8*)(lds + PG8_SA(b, h) + aoff + m * 2048 + k * 1024); } while (0)
; #define PG8_LDB(dst, b, h) do { _Pragma("unroll") for (int n = 0; n < 2; ++n) _Pragma("unroll") for (int k = 0; k < 2; ++k) dst[n][k] = *(const PG8_LAS bf16x8*)(lds + PG8_SB(b, h) + boff + n * 2048 + k * 1024); } while (0)
; #define PG8_MMA(ai, bj, At, Bt) do { __builtin_amdgcn_s_setprio(1); _Pragma("unroll") for (int m = 0; m < 4; ++m) _Pragma("unroll") for (int n = 0; n < 2; ++n) _Pragma("unroll") for (int k = 0; k < 2; ++k) \
;         acc[ai][bj][m][n] = __builtin_amdgcn_mfma_f32_16x16x32_bf16(Bt[n][k], At[m][k], acc[ai][bj][m][n], 0, 0, 0); __builtin_amdgcn_s_setprio(0); } while (0)
; #define PG8_WAIT_V(n) asm volatile("s_waitcnt vmcnt(" #n ")" ::: "memory")
; #define PG8_WAIT_L(n) asm volatile("s_waitcnt lgkmcnt(" #n ")" ::: "memory")
; #define PG8_BAR __builtin_amdgcn_s_barrier()
; #define PG8_SCHED __builtin_amdgcn_sched_barrier(0)
; template <class Epi, class Sched, bool ALIGN_EPI = false, bool SP2 = false, bool MID = false>
; __device__ __forceinline__ void gemm_phase(PG8_LAS unsigned char* lds, const Gemm g, const Sched& S, const Epi& E) {
;     ...
;             PG8_LDB(B0, 0, 0); PG8_LDB(B1, 0, 1); PG8_SCHED; PG8_LDA(At, 0, 0); PG8_STAGE(PG8_SA(1, 1), a1 + hstep, voffA);
;             PG8_WAIT_V(8); PG8_WAIT_L(0); PG8_BAR; PG8_MMA(0, 0, At, B0); PG8_MMA(0, 1, At, B1); PG8_BAR; PG8_SCHED;
;             PG8_LDA(At, 0, 1); PG8_STAGE(PG8_SB(0, 0), b2, voffB); PG8_STAGE(PG8_SB(0, 1), b2 + hstep, voffB); PG8_STAGE(PG8_SA(0, 0), a2, voffA);
;             PG8_WAIT_V(8); PG8_WAIT_L(0); PG8_BAR; PG8_MMA(1, 0, At, B0); PG8_MMA(1, 1, At, B1); PG8_BAR; PG8_SCHED;
.LBB0_1772:
	ds_read_b128 v[152:155], v149
	ds_read_b128 v[156:159], v149 offset:1024
	ds_read_b128 v[160:163], v149 offset:2048
	ds_read_b128 v[164:167], v149 offset:3072
	ds_read_b128 v[168:171], v150
	ds_read_b128 v[172:175], v150 offset:1024
	ds_read_b128 v[176:179], v150 offset:2048
	ds_read_b128 v[180:183], v150 offset:3072
	s_add_u32 s46, s44, 0xffe00080
	s_addc_u32 s47, s45, -1
	s_cmpk_eq_i32 s79, 0x7c
	s_cselect_b32 s49, s39, s47
	s_cselect_b32 s48, s75, s46
	s_cselect_b32 s47, s37, s78
	s_cselect_b32 s46, s76, s77
	v_lshl_add_u64 v[196:197], s[44:45], 0, v[138:139]
	s_add_i32 m0, s27, 0xc000
	ds_read_b128 v[184:187], v151
	ds_read_b128 v[188:191], v151 offset:1024
	ds_read_b128 v[192:195], v151 offset:2048
	ds_read_b128 v[200:203], v151 offset:3072
	ds_read_b128 v[204:207], v151 offset:4096
	ds_read_b128 v[208:211], v151 offset:5120
	ds_read_b128 v[212:215], v151 offset:6144
	ds_read_b128 v[216:219], v151 offset:7168
	global_load_lds_dwordx4 v[196:197], off
	v_lshl_add_u64 v[196:197], s[44:45], 0, v[140:141]
	s_add_i32 m0, s27, 0xe000
	s_nop 0
	global_load_lds_dwordx4 v[196:197], off
	s_waitcnt vmcnt(8)
	s_waitcnt lgkmcnt(0)
	s_barrier
	s_setprio 1
	s_waitcnt lgkmcnt(0)
	v_mfma_f32_16x16x32_bf16 v[126:129], v[152:155], v[184:187], v[126:129]
	v_mfma_f32_16x16x32_bf16 v[122:125], v[160:163], v[184:187], v[122:125]
	v_mfma_f32_16x16x32_bf16 v[118:121], v[152:155], v[192:195], v[118:121]
	v_mfma_f32_16x16x32_bf16 v[114:117], v[160:163], v[192:195], v[114:117]
	v_mfma_f32_16x16x32_bf16 v[102:105], v[152:155], v[204:207], v[102:105]
	v_mfma_f32_16x16x32_bf16 v[98:101], v[160:163], v[204:207], v[98:101]
	v_mfma_f32_16x16x32_bf16 v[86:89], v[152:155], v[212:215], v[86:89]
	v_mfma_f32_16x16x32_bf16 v[82:85], v[160:163], v[212:215], v[82:85]
	v_mfma_f32_16x16x32_bf16 v[126:129], v[156:159], v[188:191], v[126:129]
	v_mfma_f32_16x16x32_bf16 v[122:125], v[164:167], v[188:191], v[122:125]
	v_mfma_f32_16x16x32_bf16 v[118:121], v[156:159], v[200:203], v[118:121]
	v_mfma_f32_16x16x32_bf16 v[114:117], v[164:167], v[200:203], v[114:117]
	v_mfma_f32_16x16x32_bf16 v[102:105], v[156:159], v[208:211], v[102:105]
	v_mfma_f32_16x16x32_bf16 v[98:101], v[164:167], v[208:211], v[98:101]
	v_mfma_f32_16x16x32_bf16 v[86:89], v[156:159], v[216:219], v[86:89]
	v_mfma_f32_16x16x32_bf16 v[82:85], v[164:167], v[216:219], v[82:85]
	v_mfma_f32_16x16x32_bf16 v[110:113], v[168:171], v[184:187], v[110:113]
	v_mfma_f32_16x16x32_bf16 v[106:109], v[176:179], v[184:187], v[106:109]
	v_mfma_f32_16x16x32_bf16 v[94:97], v[168:171], v[192:195], v[94:97]
	v_mfma_f32_16x16x32_bf16 v[90:93], v[176:179], v[192:195], v[90:93]
	v_mfma_f32_16x16x32_bf16 v[78:81], v[168:171], v[204:207], v[78:81]
	v_mfma_f32_16x16x32_bf16 v[74:77], v[176:179], v[204:207], v[74:77]
	v_mfma_f32_16x16x32_bf16 v[70:73], v[168:171], v[212:215], v[70:73]
	v_mfma_f32_16x16x32_bf16 v[66:69], v[176:179], v[212:215], v[66:69]
	v_mfma_f32_16x16x32_bf16 v[110:113], v[172:175], v[188:191], v[110:113]
	v_mfma_f32_16x16x32_bf16 v[106:109], v[180:183], v[188:191], v[106:109]
	v_mfma_f32_16x16x32_bf16 v[94:97], v[172:175], v[200:203], v[94:97]
	v_mfma_f32_16x16x32_bf16 v[90:93], v[180:183], v[200:203], v[90:93]
	v_mfma_f32_16x16x32_bf16 v[78:81], v[172:175], v[208:211], v[78:81]
	v_mfma_f32_16x16x32_bf16 v[74:77], v[180:183], v[208:211], v[74:77]
	v_mfma_f32_16x16x32_bf16 v[70:73], v[172:175], v[216:219], v[70:73]
	v_mfma_f32_16x16x32_bf16 v[66:69], v[180:183], v[216:219], v[66:69]
	s_setprio 0
	s_barrier
	s_add_i32 s80, s59, s51
	v_lshl_add_u64 v[196:197], s[46:47], 0, v[132:133]
	s_mov_b32 m0, s80
	ds_read_b128 v[184:187], v151 offset:16384
	ds_read_b128 v[188:191], v151 offset:17408
	ds_read_b128 v[192:195], v151 offset:18432
	ds_read_b128 v[200:203], v151 offset:19456
	ds_read_b128 v[204:207], v151 offset:20480
	ds_read_b128 v[208:211], v151 offset:21504
	ds_read_b128 v[212:215], v151 offset:22528
	ds_read_b128 v[216:219], v151 offset:23552
	global_load_lds_dwordx4 v[196:197], off
	s_add_i32 m0, s80, 0x2000
	s_add_u32 s80, s46, 0x200000
	v_lshl_add_u64 v[220:221], s[46:47], 0, v[136:137]
	s_addc_u32 s81, s47, 0
	s_add_i32 s82, s62, s51
	global_load_lds_dwordx4 v[220:221], off
	v_lshl_add_u64 v[222:223], s[80:81], 0, v[132:133]
	s_mov_b32 m0, s82
	v_lshl_add_u64 v[224:225], s[48:49], 0, v[134:135]
	global_load_lds_dwordx4 v[222:223], off
	v_lshl_add_u64 v[222:223], s[80:81], 0, v[136:137]
	s_add_i32 m0, s82, 0x2000
	s_nop 0
	global_load_lds_dwordx4 v[222:223], off
	v_lshl_add_u64 v[222:223], s[48:49], 0, v[130:131]
	s_mov_b32 m0, s27
	s_nop 0
	global_load_lds_dwordx4 v[222:223], off
	s_mov_b32 m0, s52
	s_nop 0
	global_load_lds_dwordx4 v[224:225], off
	s_waitcnt vmcnt(8)
	s_waitcnt lgkmcnt(0)
	s_barrier
; #define PG8_STAGE(bufoff, gbase, voff) do { _Pragma("unroll") for (int _i = 0; _i < 2; ++_i) \
;         __builtin_amdgcn_global_load_lds((const unsigned*)((const char*)(gbase) + (voff)[_i]), (PG8_LAS unsigned*)(lds + (bufoff) + ldsw + _i * 8192), 16, 0, 0); } while (0)
; #define PG8_LDA(dst, b, h) do { _Pragma("unroll") for (int m = 0; m < 4; ++m) _Pragma("unroll") for (int k = 0; k < 2; ++k) dst[m][k] = *(const PG8_LAS bf16x8*)(lds + PG8_SA(b, h) + aoff + m * 2048 + k * 1024); } while (0)
; #define PG8_LDB(dst, b, h) do { _Pragma("unroll") for (int n = 0; n < 2; ++n) _Pragma("unroll") for (int k = 0; k < 2; ++k) dst[n][k] = *(const PG8_LAS bf16x8*)(lds + PG8_SB(b, h) + boff + n * 2048 + k * 1024); } while (0)
; #define PG8_MMA(ai, bj, At, Bt) do { __builtin_amdgcn_s_setprio(1); _Pragma("unroll") for (int m = 0; m < 4; ++m) _Pragma("unroll") for (int n = 0; n < 2; ++n) _Pragma("unroll") for (int k = 0; k < 2; ++k) \
;         acc[ai][bj][m][n] = __builtin_amdgcn_mfma_f32_16x16x32_bf16(Bt[n][k], At[m][k], acc[ai][bj][m][n], 0, 0, 0); __builtin_amdgcn_s_setprio(0); } while (0)
; #define PG8_WAIT_V(n) asm volatile("s_waitcnt vmcnt(" #n ")" ::: "memory")
; #define PG8_WAIT_L(n) asm volatile("s_waitcnt lgkmcnt(" #n ")" ::: "memory")
; #define PG8_BAR __builtin_amdgcn_s_barrier()
; #define PG8_SCHED __builtin_amdgcn_sched_barrier(0)
; template <class Epi, class Sched, bool ALIGN_EPI = false, bool SP2 = false, bool MID = false>
; __device__ __forceinline__ void gemm_phase(PG8_LAS unsigned char* lds, const Gemm g, const Sched& S, const Epi& E) {
;     ...
;             PG8_WAIT_V(8); PG8_WAIT_L(0); PG8_BAR; PG8_MMA(1, 0, At, B0); PG8_MMA(1, 1, At, B1); PG8_BAR; PG8_SCHED;
;             PG8_LDB(B0, 1, 0); PG8_LDB(B1, 1, 1); PG8_SCHED; PG8_LDA(At, 1, 0); PG8_STAGE(PG8_SA(0, 1), a2 + hstep, voffA);
;             PG8_WAIT_V(8); PG8_WAIT_L(0); PG8_BAR; PG8_MMA(0, 0, At, B0); PG8_MMA(0, 1, At, B1); PG8_BAR; PG8_SCHED;
	s_setprio 1
	s_waitcnt lgkmcnt(0)
	v_mfma_f32_16x16x32_bf16 v[62:65], v[152:155], v[184:187], v[62:65]
	v_mfma_f32_16x16x32_bf16 v[58:61], v[160:163], v[184:187], v[58:61]
	v_mfma_f32_16x16x32_bf16 v[54:57], v[152:155], v[192:195], v[54:57]
	v_mfma_f32_16x16x32_bf16 v[50:53], v[160:163], v[192:195], v[50:53]
	v_mfma_f32_16x16x32_bf16 v[38:41], v[152:155], v[204:207], v[38:41]
	v_mfma_f32_16x16x32_bf16 v[34:37], v[160:163], v[204:207], v[34:37]
	v_mfma_f32_16x16x32_bf16 v[22:25], v[152:155], v[212:215], v[22:25]
	v_mfma_f32_16x16x32_bf16 v[18:21], v[160:163], v[212:215], v[18:21]
	v_mfma_f32_16x16x32_bf16 v[62:65], v[156:159], v[188:191], v[62:65]
	v_mfma_f32_16x16x32_bf16 v[58:61], v[164:167], v[188:191], v[58:61]
	v_mfma_f32_16x16x32_bf16 v[54:57], v[156:159], v[200:203], v[54:57]
	v_mfma_f32_16x16x32_bf16 v[50:53], v[164:167], v[200:203], v[50:53]
	v_mfma_f32_16x16x32_bf16 v[38:41], v[156:159], v[208:211], v[38:41]
	v_mfma_f32_16x16x32_bf16 v[34:37], v[164:167], v[208:211], v[34:37]
	v_mfma_f32_16x16x32_bf16 v[22:25], v[156:159], v[216:219], v[22:25]
	v_mfma_f32_16x16x32_bf16 v[18:21], v[164:167], v[216:219], v[18:21]
	v_mfma_f32_16x16x32_bf16 v[46:49], v[168:171], v[184:187], v[46:49]
	v_mfma_f32_16x16x32_bf16 v[42:45], v[176:179], v[184:187], v[42:45]
	v_mfma_f32_16x16x32_bf16 v[30:33], v[168:171], v[192:195], v[30:33]
	v_mfma_f32_16x16x32_bf16 v[26:29], v[176:179], v[192:195], v[26:29]
	v_mfma_f32_16x16x32_bf16 v[14:17], v[168:171], v[204:207], v[14:17]
	v_mfma_f32_16x16x32_bf16 v[10:13], v[176:179], v[204:207], v[10:13]
	v_mfma_f32_16x16x32_bf16 v[6:9], v[168:171], v[212:215], v[6:9]
	v_mfma_f32_16x16x32_bf16 v[2:5], v[176:179], v[212:215], v[2:5]
	v_mfma_f32_16x16x32_bf16 v[46:49], v[172:175], v[188:191], v[46:49]
	v_mfma_f32_16x16x32_bf16 v[42:45], v[180:183], v[188:191], v[42:45]
	v_mfma_f32_16x16x32_bf16 v[30:33], v[172:175], v[200:203], v[30:33]
	v_mfma_f32_16x16x32_bf16 v[26:29], v[180:183], v[200:203], v[26:29]
	v_mfma_f32_16x16x32_bf16 v[14:17], v[172:175], v[208:211], v[14:17]
	v_mfma_f32_16x16x32_bf16 v[10:13], v[180:183], v[208:211], v[10:13]
	v_mfma_f32_16x16x32_bf16 v[6:9], v[172:175], v[216:219], v[6:9]
	v_mfma_f32_16x16x32_bf16 v[2:5], v[180:183], v[216:219], v[2:5]
	s_setprio 0
	s_barrier
	s_add_i32 s80, 0, 0x18000
	s_add_i32 s81, 0, 0x1c000
	v_add_u32_e32 v164, s80, v147
	v_add_u32_e32 v180, s81, v147
	ds_read_b128 v[152:155], v164
	ds_read_b128 v[156:159], v164 offset:1024
	ds_read_b128 v[160:163], v164 offset:2048
	ds_read_b128 v[164:167], v164 offset:3072
	ds_read_b128 v[168:171], v180
	ds_read_b128 v[172:175], v180 offset:1024
	ds_read_b128 v[176:179], v180 offset:2048
	ds_read_b128 v[180:183], v180 offset:3072
	s_add_u32 s48, s48, 0x200000
	s_addc_u32 s49, s49, 0
	s_mov_b32 m0, s53
	v_lshl_add_u64 v[226:227], s[48:49], 0, v[130:131]
	ds_read_b128 v[184:187], v151 offset:32768
	ds_read_b128 v[188:191], v151 offset:33792
	ds_read_b128 v[192:195], v151 offset:34816
	ds_read_b128 v[200:203], v151 offset:35840
	ds_read_b128 v[204:207], v151 offset:36864
	ds_read_b128 v[208:211], v151 offset:37888
	ds_read_b128 v[212:215], v151 offset:38912
	ds_read_b128 v[216:219], v151 offset:39936
	global_load_lds_dwordx4 v[226:227], off
	v_lshl_add_u64 v[226:227], s[48:49], 0, v[134:135]
	s_mov_b32 m0, s54
	s_nop 0
	global_load_lds_dwordx4 v[226:227], off
	s_waitcnt vmcnt(8)
	s_waitcnt lgkmcnt(0)
	s_barrier
	s_setprio 1
	s_waitcnt lgkmcnt(0)
	v_mfma_f32_16x16x32_bf16 v[126:129], v[152:155], v[184:187], v[126:129]
	v_mfma_f32_16x16x32_bf16 v[122:125], v[160:163], v[184:187], v[122:125]
	v_mfma_f32_16x16x32_bf16 v[118:121], v[152:155], v[192:195], v[118:121]
	v_mfma_f32_16x16x32_bf16 v[114:117], v[160:163], v[192:195], v[114:117]
	v_mfma_f32_16x16x32_bf16 v[102:105], v[152:155], v[204:207], v[102:105]
	v_mfma_f32_16x16x32_bf16 v[98:101], v[160:163], v[204:207], v[98:101]
	v_mfma_f32_16x16x32_bf16 v[86:89], v[152:155], v[212:215], v[86:89]
	v_mfma_f32_16x16x32_bf16 v[82:85], v[160:163], v[212:215], v[82:85]
	v_mfma_f32_16x16x32_bf16 v[126:129], v[156:159], v[188:191], v[126:129]
	v_mfma_f32_16x16x32_bf16 v[122:125], v[164:167], v[188:191], v[122:125]
	v_mfma_f32_16x16x32_bf16 v[118:121], v[156:159], v[200:203], v[118:121]
	v_mfma_f32_16x16x32_bf16 v[114:117], v[164:167], v[200:203], v[114:117]
	v_mfma_f32_16x16x32_bf16 v[102:105], v[156:159], v[208:211], v[102:105]
	v_mfma_f32_16x16x32_bf16 v[98:101], v[164:167], v[208:211], v[98:101]
	v_mfma_f32_16x16x32_bf16 v[86:89], v[156:159], v[216:219], v[86:89]
	v_mfma_f32_16x16x32_bf16 v[82:85], v[164:167], v[216:219], v[82:85]
	v_mfma_f32_16x16x32_bf16 v[110:113], v[168:171], v[184:187], v[110:113]
	v_mfma_f32_16x16x32_bf16 v[106:109], v[176:179], v[184:187], v[106:109]
	v_mfma_f32_16x16x32_bf16 v[94:97], v[168:171], v[192:195], v[94:97]
	v_mfma_f32_16x16x32_bf16 v[90:93], v[176:179], v[192:195], v[90:93]
	v_mfma_f32_16x16x32_bf16 v[78:81], v[168:171], v[204:207], v[78:81]
	v_mfma_f32_16x16x32_bf16 v[74:77], v[176:179], v[204:207], v[74:77]
	v_mfma_f32_16x16x32_bf16 v[70:73], v[168:171], v[212:215], v[70:73]
	v_mfma_f32_16x16x32_bf16 v[66:69], v[176:179], v[212:215], v[66:69]
	v_mfma_f32_16x16x32_bf16 v[110:113], v[172:175], v[188:191], v[110:113]
	v_mfma_f32_16x16x32_bf16 v[106:109], v[180:183], v[188:191], v[106:109]
	v_mfma_f32_16x16x32_bf16 v[94:97], v[172:175], v[200:203], v[94:97]
	v_mfma_f32_16x16x32_bf16 v[90:93], v[180:183], v[200:203], v[90:93]
	v_mfma_f32_16x16x32_bf16 v[78:81], v[172:175], v[208:211], v[78:81]
	v_mfma_f32_16x16x32_bf16 v[74:77], v[180:183], v[208:211], v[74:77]
	v_mfma_f32_16x16x32_bf16 v[70:73], v[172:175], v[216:219], v[70:73]
	v_mfma_f32_16x16x32_bf16 v[66:69], v[180:183], v[216:219], v[66:69]
	s_setprio 0
	s_barrier
; #define PG8_STAGE(bufoff, gbase, voff) do { _Pragma("unroll") for (int _i = 0; _i < 2; ++_i) \
;         __builtin_amdgcn_global_load_lds((const unsigned*)((const char*)(gbase) + (voff)[_i]), (PG8_LAS unsigned*)(lds + (bufoff) + ldsw + _i * 8192), 16, 0, 0); } while (0)
; #define PG8_LDA(dst, b, h) do { _Pragma("unroll") for (int m = 0; m < 4; ++m) _Pragma("unroll") for (int k = 0; k < 2; ++k) dst[m][k] = *(const PG8_LAS bf16x8*)(lds + PG8_SA(b, h) + aoff + m * 2048 + k * 1024); } while (0)
; #define PG8_MMA(ai, bj, At, Bt) do { __builtin_amdgcn_s_setprio(1); _Pragma("unroll") for (int m = 0; m < 4; ++m) _Pragma("unroll") for (int n = 0; n < 2; ++n) _Pragma("unroll") for (int k = 0; k < 2; ++k) \
;         acc[ai][bj][m][n] = __builtin_amdgcn_mfma_f32_16x16x32_bf16(Bt[n][k], At[m][k], acc[ai][bj][m][n], 0, 0, 0); __builtin_amdgcn_s_setprio(0); } while (0)
; #define PG8_WAIT_V(n) asm volatile("s_waitcnt vmcnt(" #n ")" ::: "memory")
; #define PG8_WAIT_L(n) asm volatile("s_waitcnt lgkmcnt(" #n ")" ::: "memory")
; #define PG8_BAR __builtin_amdgcn_s_barrier()
; #define PG8_SCHED __builtin_amdgcn_sched_barrier(0)
; template <class Epi, class Sched, bool ALIGN_EPI = false, bool SP2 = false, bool MID = false>
; __device__ __forceinline__ void gemm_phase(PG8_LAS unsigned char* lds, const Gemm g, const Sched& S, const Epi& E) {
;     ...
;         for (int t = 0; t < nt; t += 2) {
;             const bool last = (t == nt - 2);
;             if constexpr (MID) { if (t == Epi::MID_T) { PG8_SCHED; E.mid(acc, cur, wr, wc, fr, fq); PG8_SCHED; } }
;             const char* a1 = cA + (size_t)(t + 1) * kstep;
;             const char* a2 = last ? nA : cA + (size_t)(t + 2) * kstep; const char* b2 = last ? nB : cB + (size_t)(t + 2) * kstep;
;             const char* a3 = a2 + kstep; const char* b3 = b2 + kstep;
;             if (last && has_next) S.a_ready(nxt);
;     ...
;             PG8_LDA(At, 1, 1); PG8_STAGE(PG8_SB(1, 0), b3, voffB); PG8_STAGE(PG8_SB(1, 1), b3 + hstep, voffB); PG8_STAGE(PG8_SA(1, 0), a3, voffA);
;             PG8_WAIT_V(8); PG8_WAIT_L(0); PG8_BAR; PG8_MMA(1, 0, At, B0); PG8_MMA(1, 1, At, B1); PG8_BAR; PG8_SCHED;
	s_add_i32 s48, s80, s51
	v_lshl_add_u64 v[196:197], v[196:197], 0, s[12:13]
	s_mov_b32 m0, s48
	ds_read_b128 v[184:187], v151 offset:49152
	ds_read_b128 v[188:191], v151 offset:50176
	ds_read_b128 v[192:195], v151 offset:51200
	ds_read_b128 v[200:203], v151 offset:52224
	ds_read_b128 v[204:207], v151 offset:53248
	ds_read_b128 v[208:211], v151 offset:54272
	ds_read_b128 v[212:215], v151 offset:55296
	ds_read_b128 v[216:219], v151 offset:56320
	global_load_lds_dwordx4 v[196:197], off
	s_add_i32 m0, s48, 0x2000
	s_add_u32 s46, s46, 0x200080
	v_lshl_add_u64 v[196:197], v[220:221], 0, s[12:13]
	s_addc_u32 s47, s47, 0
	s_add_i32 s48, s81, s51
	global_load_lds_dwordx4 v[196:197], off
	v_lshl_add_u64 v[196:197], s[46:47], 0, v[132:133]
	s_mov_b32 m0, s48
	s_nop 0
	global_load_lds_dwordx4 v[196:197], off
	v_lshl_add_u64 v[196:197], s[46:47], 0, v[136:137]
	s_add_i32 m0, s48, 0x2000
	s_nop 0
	global_load_lds_dwordx4 v[196:197], off
	v_lshl_add_u64 v[196:197], v[222:223], 0, s[12:13]
	s_mov_b32 m0, s56
	s_nop 0
	global_load_lds_dwordx4 v[196:197], off
	v_lshl_add_u64 v[196:197], v[224:225], 0, s[12:13]
	s_mov_b32 m0, s57
	s_nop 0
	global_load_lds_dwordx4 v[196:197], off
	s_waitcnt vmcnt(8)
	s_waitcnt lgkmcnt(0)
	s_barrier
	s_setprio 1
	s_waitcnt lgkmcnt(0)
	v_mfma_f32_16x16x32_bf16 v[62:65], v[152:155], v[184:187], v[62:65]
	v_mfma_f32_16x16x32_bf16 v[58:61], v[160:163], v[184:187], v[58:61]
	v_mfma_f32_16x16x32_bf16 v[54:57], v[152:155], v[192:195], v[54:57]
	v_mfma_f32_16x16x32_bf16 v[50:53], v[160:163], v[192:195], v[50:53]
	v_mfma_f32_16x16x32_bf16 v[38:41], v[152:155], v[204:207], v[38:41]
	v_mfma_f32_16x16x32_bf16 v[34:37], v[160:163], v[204:207], v[34:37]
	v_mfma_f32_16x16x32_bf16 v[22:25], v[152:155], v[212:215], v[22:25]
	v_mfma_f32_16x16x32_bf16 v[18:21], v[160:163], v[212:215], v[18:21]
	v_mfma_f32_16x16x32_bf16 v[62:65], v[156:159], v[188:191], v[62:65]
	v_mfma_f32_16x16x32_bf16 v[58:61], v[164:167], v[188:191], v[58:61]
	v_mfma_f32_16x16x32_bf16 v[54:57], v[156:159], v[200:203], v[54:57]
	v_mfma_f32_16x16x32_bf16 v[50:53], v[164:167], v[200:203], v[50:53]
	v_mfma_f32_16x16x32_bf16 v[38:41], v[156:159], v[208:211], v[38:41]
	v_mfma_f32_16x16x32_bf16 v[34:37], v[164:167], v[208:211], v[34:37]
	v_mfma_f32_16x16x32_bf16 v[22:25], v[156:159], v[216:219], v[22:25]
	v_mfma_f32_16x16x32_bf16 v[18:21], v[164:167], v[216:219], v[18:21]
	v_mfma_f32_16x16x32_bf16 v[46:49], v[168:171], v[184:187], v[46:49]
	v_mfma_f32_16x16x32_bf16 v[42:45], v[176:179], v[184:187], v[42:45]
	v_mfma_f32_16x16x32_bf16 v[30:33], v[168:171], v[192:195], v[30:33]
	v_mfma_f32_16x16x32_bf16 v[26:29], v[176:179], v[192:195], v[26:29]
	v_mfma_f32_16x16x32_bf16 v[14:17], v[168:171], v[204:207], v[14:17]
	v_mfma_f32_16x16x32_bf16 v[10:13], v[176:179], v[204:207], v[10:13]
	v_mfma_f32_16x16x32_bf16 v[6:9], v[168:171], v[212:215], v[6:9]
	v_mfma_f32_16x16x32_bf16 v[2:5], v[176:179], v[212:215], v[2:5]
	v_mfma_f32_16x16x32_bf16 v[46:49], v[172:175], v[188:191], v[46:49]
	v_mfma_f32_16x16x32_bf16 v[42:45], v[180:183], v[188:191], v[42:45]
	v_mfma_f32_16x16x32_bf16 v[30:33], v[172:175], v[200:203], v[30:33]
	v_mfma_f32_16x16x32_bf16 v[26:29], v[180:183], v[200:203], v[26:29]
	v_mfma_f32_16x16x32_bf16 v[14:17], v[172:175], v[208:211], v[14:17]
	v_mfma_f32_16x16x32_bf16 v[10:13], v[180:183], v[208:211], v[10:13]
	v_mfma_f32_16x16x32_bf16 v[6:9], v[172:175], v[216:219], v[6:9]
	v_mfma_f32_16x16x32_bf16 v[2:5], v[180:183], v[216:219], v[2:5]
	s_setprio 0
	s_barrier
	s_add_i32 s79, s79, 2
	s_add_u32 s44, s44, 0x100
	s_addc_u32 s45, s45, 0
	s_add_u32 s77, s77, 0x100
	s_addc_u32 s78, s78, 0
	s_cmpk_gt_u32 s79, 0x7d
	s_cbranch_scc0 .LBB0_1772
	s_and_b64 vcc, exec, s[16:17]
	s_cbranch_vccz .LBB0_1775
	s_barrier

; #define PG8_STAGE(bufoff, gbase, voff) do { _Pragma("unroll") for (int _i = 0; _i < 2; ++_i) \
;         __builtin_amdgcn_global_load_lds((const unsigned*)((const char*)(gbase) + (voff)[_i]), (PG8_LAS unsigned*)(lds + (bufoff) + ldsw + _i * 8192), 16, 0, 0); } while (0)
; #define PG8_LDA(dst, b, h) do { _Pragma("unroll") for (int m = 0; m < 4; ++m) _Pragma("unroll") for (int k = 0; k < 2; ++k) dst[m][k] = *(const PG8_LAS bf16x8*)(lds + PG8_SA(b, h) + aoff + m * 2048 + k * 1024); } while (0)
; #define PG8_LDB(dst, b, h) do { _Pragma("unroll") for (int n = 0; n < 2; ++n) _Pragma("unroll") for (int k = 0; k < 2; ++k) dst[n][k] = *(const PG8_LAS bf16x8*)(lds + PG8_SB(b, h) + boff + n * 2048 + k * 1024); } while (0)
; #define PG8_MMA(ai, bj, At, Bt) do { __builtin_amdgcn_s_setprio(1); _Pragma("unroll") for (int m = 0; m < 4; ++m) _Pragma("unroll") for (int n = 0; n < 2; ++n) _Pragma("unroll") for (int k = 0; k < 2; ++k) \
;         acc[ai][bj][m][n] = __builtin_amdgcn_mfma_f32_16x16x32_bf16(Bt[n][k], At[m][k], acc[ai][bj][m][n], 0, 0, 0); __builtin_amdgcn_s_setprio(0); } while (0)
; #define PG8_WAIT_V(n) asm volatile("s_waitcnt vmcnt(" #n ")" ::: "memory")
; #define PG8_WAIT_L(n) asm volatile("s_waitcnt lgkmcnt(" #n ")" ::: "memory")
; #define PG8_BAR __builtin_amdgcn_s_barrier()
; #define PG8_SCHED __builtin_amdgcn_sched_barrier(0)
; template <class Epi, class Sched, bool ALIGN_EPI = false, bool SP2 = false, bool MID = false>
; __device__ __forceinline__ void gemm_phase(PG8_LAS unsigned char* lds, const Gemm g, const Sched& S, const Epi& E) {
;     ...
;             PG8_LDB(B0, 0, 0); PG8_LDB(B1, 0, 1); PG8_SCHED; PG8_LDA(At, 0, 0); PG8_STAGE(PG8_SA(1, 1), a1 + hstep, voffA);
;             PG8_WAIT_V(8); PG8_WAIT_L(0); PG8_BAR; PG8_MMA(0, 0, At, B0); PG8_MMA(0, 1, At, B1); PG8_BAR; PG8_SCHED;
;             PG8_LDA(At, 0, 1); PG8_STAGE(PG8_SB(0, 0), b2, voffB); PG8_STAGE(PG8_SB(0, 1), b2 + hstep, voffB); PG8_STAGE(PG8_SA(0, 0), a2, voffA);
;             PG8_WAIT_V(8); PG8_WAIT_L(0); PG8_BAR; PG8_MMA(1, 0, At, B0); PG8_MMA(1, 1, At, B1); PG8_BAR; PG8_SCHED;
.LBB0_1937:
	s_add_u32 s26, s22, s24
	s_addc_u32 s27, s23, s25
	s_add_u32 s26, s26, 0x100
	s_addc_u32 s27, s27, 0
	s_add_u32 s73, s62, s24
	s_addc_u32 s74, s70, s25
	s_add_i32 s72, 0, 0x10000
	v_add_u32_e32 v133, s72, v161
	ds_read_b128 v[156:159], v133
	ds_read_b128 v[164:167], v133 offset:1024
	ds_read_b128 v[168:171], v133 offset:2048
	ds_read_b128 v[172:175], v133 offset:3072
	v_add_u32_e32 v133, s57, v161
	ds_read_b128 v[176:179], v133
	ds_read_b128 v[180:183], v133 offset:1024
	ds_read_b128 v[184:187], v133 offset:2048
	ds_read_b128 v[188:191], v133 offset:3072
	s_cmpk_eq_i32 s24, 0x1100
	s_cselect_b32 s37, s5, s27
	s_cselect_b32 s36, s4, s26
	s_cselect_b32 s27, s21, s74
	s_cselect_b32 s26, s20, s73
	v_lshl_add_u64 v[196:197], v[152:153], 0, s[24:25]
	s_add_i32 m0, s42, 0xc000
	ds_read_b128 v[192:195], v163
	ds_read_b128 v[200:203], v163 offset:1024
	ds_read_b128 v[204:207], v163 offset:2048
	ds_read_b128 v[208:211], v163 offset:3072
	ds_read_b128 v[212:215], v163 offset:4096
	ds_read_b128 v[216:219], v163 offset:5120
	ds_read_b128 v[220:223], v163 offset:6144
	ds_read_b128 v[224:227], v163 offset:7168
	global_load_lds_dwordx4 v[196:197], off
	v_lshl_add_u64 v[196:197], v[154:155], 0, s[24:25]
	s_add_i32 m0, s42, 0xe000
	s_nop 0
	global_load_lds_dwordx4 v[196:197], off
	s_waitcnt vmcnt(8)
	s_waitcnt lgkmcnt(0)
	s_barrier
	s_setprio 1
	s_waitcnt lgkmcnt(0)
	v_mfma_f32_16x16x32_bf16 v[126:129], v[156:159], v[192:195], v[126:129]
	v_mfma_f32_16x16x32_bf16 v[122:125], v[168:171], v[192:195], v[122:125]
	v_mfma_f32_16x16x32_bf16 v[110:113], v[156:159], v[204:207], v[110:113]
	v_mfma_f32_16x16x32_bf16 v[106:109], v[168:171], v[204:207], v[106:109]
	v_mfma_f32_16x16x32_bf16 v[94:97], v[156:159], v[212:215], v[94:97]
	v_mfma_f32_16x16x32_bf16 v[90:93], v[168:171], v[212:215], v[90:93]
	v_mfma_f32_16x16x32_bf16 v[78:81], v[156:159], v[220:223], v[78:81]
	v_mfma_f32_16x16x32_bf16 v[74:77], v[168:171], v[220:223], v[74:77]
	v_mfma_f32_16x16x32_bf16 v[126:129], v[164:167], v[200:203], v[126:129]
	v_mfma_f32_16x16x32_bf16 v[122:125], v[172:175], v[200:203], v[122:125]
	v_mfma_f32_16x16x32_bf16 v[110:113], v[164:167], v[208:211], v[110:113]
	v_mfma_f32_16x16x32_bf16 v[106:109], v[172:175], v[208:211], v[106:109]
	v_mfma_f32_16x16x32_bf16 v[94:97], v[164:167], v[216:219], v[94:97]
	v_mfma_f32_16x16x32_bf16 v[90:93], v[172:175], v[216:219], v[90:93]
	v_mfma_f32_16x16x32_bf16 v[78:81], v[164:167], v[224:227], v[78:81]
	v_mfma_f32_16x16x32_bf16 v[74:77], v[172:175], v[224:227], v[74:77]
	v_mfma_f32_16x16x32_bf16 v[118:121], v[176:179], v[192:195], v[118:121]
	v_mfma_f32_16x16x32_bf16 v[114:117], v[184:187], v[192:195], v[114:117]
	v_mfma_f32_16x16x32_bf16 v[102:105], v[176:179], v[204:207], v[102:105]
	v_mfma_f32_16x16x32_bf16 v[98:101], v[184:187], v[204:207], v[98:101]
	v_mfma_f32_16x16x32_bf16 v[86:89], v[176:179], v[212:215], v[86:89]
	v_mfma_f32_16x16x32_bf16 v[82:85], v[184:187], v[212:215], v[82:85]
	v_mfma_f32_16x16x32_bf16 v[70:73], v[176:179], v[220:223], v[70:73]
	v_mfma_f32_16x16x32_bf16 v[66:69], v[184:187], v[220:223], v[66:69]
	v_mfma_f32_16x16x32_bf16 v[118:121], v[180:183], v[200:203], v[118:121]
	v_mfma_f32_16x16x32_bf16 v[114:117], v[188:191], v[200:203], v[114:117]
	v_mfma_f32_16x16x32_bf16 v[102:105], v[180:183], v[208:211], v[102:105]
	v_mfma_f32_16x16x32_bf16 v[98:101], v[188:191], v[208:211], v[98:101]
	v_mfma_f32_16x16x32_bf16 v[86:89], v[180:183], v[216:219], v[86:89]
	v_mfma_f32_16x16x32_bf16 v[82:85], v[188:191], v[216:219], v[82:85]
	v_mfma_f32_16x16x32_bf16 v[70:73], v[180:183], v[224:227], v[70:73]
	v_mfma_f32_16x16x32_bf16 v[66:69], v[188:191], v[224:227], v[66:69]
	s_setprio 0
	s_barrier
	s_add_i32 s72, s72, s41
	v_lshl_add_u64 v[196:197], s[26:27], 0, v[136:137]
	s_mov_b32 m0, s72
	ds_read_b128 v[192:195], v163 offset:16384
	ds_read_b128 v[200:203], v163 offset:17408
	ds_read_b128 v[204:207], v163 offset:18432
	ds_read_b128 v[208:211], v163 offset:19456
	ds_read_b128 v[212:215], v163 offset:20480
	ds_read_b128 v[216:219], v163 offset:21504
	ds_read_b128 v[220:223], v163 offset:22528
	ds_read_b128 v[224:227], v163 offset:23552
	global_load_lds_dwordx4 v[196:197], off
	s_add_i32 m0, s72, 0x2000
	s_add_u32 s72, s26, 0x90000
	v_lshl_add_u64 v[228:229], s[26:27], 0, v[140:141]
	s_addc_u32 s73, s27, 0
	s_add_i32 s74, s57, s41
	global_load_lds_dwordx4 v[228:229], off
	v_lshl_add_u64 v[230:231], s[72:73], 0, v[136:137]
	s_mov_b32 m0, s74
	v_lshl_add_u64 v[232:233], s[36:37], 0, v[138:139]
	global_load_lds_dwordx4 v[230:231], off
	v_lshl_add_u64 v[230:231], s[72:73], 0, v[140:141]
	s_add_i32 m0, s74, 0x2000
	s_nop 0
	global_load_lds_dwordx4 v[230:231], off
	v_lshl_add_u64 v[230:231], s[36:37], 0, v[134:135]
	s_mov_b32 m0, s42
	s_nop 0
	global_load_lds_dwordx4 v[230:231], off
	s_mov_b32 m0, s43
	s_nop 0
	global_load_lds_dwordx4 v[232:233], off
	s_waitcnt vmcnt(8)
	s_waitcnt lgkmcnt(0)
	s_barrier
; #define PG8_STAGE(bufoff, gbase, voff) do { _Pragma("unroll") for (int _i = 0; _i < 2; ++_i) \
;         __builtin_amdgcn_global_load_lds((const unsigned*)((const char*)(gbase) + (voff)[_i]), (PG8_LAS unsigned*)(lds + (bufoff) + ldsw + _i * 8192), 16, 0, 0); } while (0)
; #define PG8_LDA(dst, b, h) do { _Pragma("unroll") for (int m = 0; m < 4; ++m) _Pragma("unroll") for (int k = 0; k < 2; ++k) dst[m][k] = *(const PG8_LAS bf16x8*)(lds + PG8_SA(b, h) + aoff + m * 2048 + k * 1024); } while (0)
; #define PG8_LDB(dst, b, h) do { _Pragma("unroll") for (int n = 0; n < 2; ++n) _Pragma("unroll") for (int k = 0; k < 2; ++k) dst[n][k] = *(const PG8_LAS bf16x8*)(lds + PG8_SB(b, h) + boff + n * 2048 + k * 1024); } while (0)
; #define PG8_MMA(ai, bj, At, Bt) do { __builtin_amdgcn_s_setprio(1); _Pragma("unroll") for (int m = 0; m < 4; ++m) _Pragma("unroll") for (int n = 0; n < 2; ++n) _Pragma("unroll") for (int k = 0; k < 2; ++k) \
;         acc[ai][bj][m][n] = __builtin_amdgcn_mfma_f32_16x16x32_bf16(Bt[n][k], At[m][k], acc[ai][bj][m][n], 0, 0, 0); __builtin_amdgcn_s_setprio(0); } while (0)
; #define PG8_WAIT_V(n) asm volatile("s_waitcnt vmcnt(" #n ")" ::: "memory")
; #define PG8_WAIT_L(n) asm volatile("s_waitcnt lgkmcnt(" #n ")" ::: "memory")
; #define PG8_BAR __builtin_amdgcn_s_barrier()
; #define PG8_SCHED __builtin_amdgcn_sched_barrier(0)
; template <class Epi, class Sched, bool ALIGN_EPI = false, bool SP2 = false, bool MID = false>
; __device__ __forceinline__ void gemm_phase(PG8_LAS unsigned char* lds, const Gemm g, const Sched& S, const Epi& E) {
;     ...
;             PG8_WAIT_V(8); PG8_WAIT_L(0); PG8_BAR; PG8_MMA(1, 0, At, B0); PG8_MMA(1, 1, At, B1); PG8_BAR; PG8_SCHED;
;             PG8_LDB(B0, 1, 0); PG8_LDB(B1, 1, 1); PG8_SCHED; PG8_LDA(At, 1, 0); PG8_STAGE(PG8_SA(0, 1), a2 + hstep, voffA);
;             PG8_WAIT_V(8); PG8_WAIT_L(0); PG8_BAR; PG8_MMA(0, 0, At, B0); PG8_MMA(0, 1, At, B1); PG8_BAR; PG8_SCHED;
	s_setprio 1
	s_waitcnt lgkmcnt(0)
	v_mfma_f32_16x16x32_bf16 v[62:65], v[156:159], v[192:195], v[62:65]
	v_mfma_f32_16x16x32_bf16 v[58:61], v[168:171], v[192:195], v[58:61]
	v_mfma_f32_16x16x32_bf16 v[46:49], v[156:159], v[204:207], v[46:49]
	v_mfma_f32_16x16x32_bf16 v[42:45], v[168:171], v[204:207], v[42:45]
	v_mfma_f32_16x16x32_bf16 v[30:33], v[156:159], v[212:215], v[30:33]
	v_mfma_f32_16x16x32_bf16 v[26:29], v[168:171], v[212:215], v[26:29]
	v_mfma_f32_16x16x32_bf16 v[14:17], v[156:159], v[220:223], v[14:17]
	v_mfma_f32_16x16x32_bf16 v[10:13], v[168:171], v[220:223], v[10:13]
	v_mfma_f32_16x16x32_bf16 v[62:65], v[164:167], v[200:203], v[62:65]
	v_mfma_f32_16x16x32_bf16 v[58:61], v[172:175], v[200:203], v[58:61]
	v_mfma_f32_16x16x32_bf16 v[46:49], v[164:167], v[208:211], v[46:49]
	v_mfma_f32_16x16x32_bf16 v[42:45], v[172:175], v[208:211], v[42:45]
	v_mfma_f32_16x16x32_bf16 v[30:33], v[164:167], v[216:219], v[30:33]
	v_mfma_f32_16x16x32_bf16 v[26:29], v[172:175], v[216:219], v[26:29]
	v_mfma_f32_16x16x32_bf16 v[14:17], v[164:167], v[224:227], v[14:17]
	v_mfma_f32_16x16x32_bf16 v[10:13], v[172:175], v[224:227], v[10:13]
	v_mfma_f32_16x16x32_bf16 v[54:57], v[176:179], v[192:195], v[54:57]
	v_mfma_f32_16x16x32_bf16 v[50:53], v[184:187], v[192:195], v[50:53]
	v_mfma_f32_16x16x32_bf16 v[38:41], v[176:179], v[204:207], v[38:41]
	v_mfma_f32_16x16x32_bf16 v[34:37], v[184:187], v[204:207], v[34:37]
	v_mfma_f32_16x16x32_bf16 v[22:25], v[176:179], v[212:215], v[22:25]
	v_mfma_f32_16x16x32_bf16 v[18:21], v[184:187], v[212:215], v[18:21]
	v_mfma_f32_16x16x32_bf16 v[6:9], v[176:179], v[220:223], v[6:9]
	v_mfma_f32_16x16x32_bf16 v[2:5], v[184:187], v[220:223], v[2:5]
	v_mfma_f32_16x16x32_bf16 v[54:57], v[180:183], v[200:203], v[54:57]
	v_mfma_f32_16x16x32_bf16 v[50:53], v[188:191], v[200:203], v[50:53]
	v_mfma_f32_16x16x32_bf16 v[38:41], v[180:183], v[208:211], v[38:41]
	v_mfma_f32_16x16x32_bf16 v[34:37], v[188:191], v[208:211], v[34:37]
	v_mfma_f32_16x16x32_bf16 v[22:25], v[180:183], v[216:219], v[22:25]
	v_mfma_f32_16x16x32_bf16 v[18:21], v[188:191], v[216:219], v[18:21]
	v_mfma_f32_16x16x32_bf16 v[6:9], v[180:183], v[224:227], v[6:9]
	v_mfma_f32_16x16x32_bf16 v[2:5], v[188:191], v[224:227], v[2:5]
	s_setprio 0
	s_barrier
	s_add_i32 s72, 0, 0x18000
	v_add_u32_e32 v133, s72, v161
	s_add_i32 s73, 0, 0x1c000
	ds_read_b128 v[156:159], v133
	ds_read_b128 v[164:167], v133 offset:1024
	ds_read_b128 v[168:171], v133 offset:2048
	ds_read_b128 v[172:175], v133 offset:3072
	v_add_u32_e32 v133, s73, v161
	ds_read_b128 v[176:179], v133
	ds_read_b128 v[180:183], v133 offset:1024
	ds_read_b128 v[184:187], v133 offset:2048
	ds_read_b128 v[188:191], v133 offset:3072
	s_add_u32 s36, s36, 0x90000
	s_addc_u32 s37, s37, 0
	s_mov_b32 m0, s44
	v_lshl_add_u64 v[234:235], s[36:37], 0, v[134:135]
	ds_read_b128 v[192:195], v163 offset:32768
	ds_read_b128 v[200:203], v163 offset:33792
	ds_read_b128 v[204:207], v163 offset:34816
	ds_read_b128 v[208:211], v163 offset:35840
	ds_read_b128 v[212:215], v163 offset:36864
	ds_read_b128 v[216:219], v163 offset:37888
	ds_read_b128 v[220:223], v163 offset:38912
	ds_read_b128 v[224:227], v163 offset:39936
	global_load_lds_dwordx4 v[234:235], off
	v_lshl_add_u64 v[234:235], s[36:37], 0, v[138:139]
	s_mov_b32 m0, s45
	s_nop 0
	global_load_lds_dwordx4 v[234:235], off
	s_waitcnt vmcnt(8)
	s_waitcnt lgkmcnt(0)
	s_barrier
	s_setprio 1
	s_waitcnt lgkmcnt(0)
	v_mfma_f32_16x16x32_bf16 v[126:129], v[156:159], v[192:195], v[126:129]
	v_mfma_f32_16x16x32_bf16 v[122:125], v[168:171], v[192:195], v[122:125]
	v_mfma_f32_16x16x32_bf16 v[110:113], v[156:159], v[204:207], v[110:113]
	v_mfma_f32_16x16x32_bf16 v[106:109], v[168:171], v[204:207], v[106:109]
	v_mfma_f32_16x16x32_bf16 v[94:97], v[156:159], v[212:215], v[94:97]
	v_mfma_f32_16x16x32_bf16 v[90:93], v[168:171], v[212:215], v[90:93]
	v_mfma_f32_16x16x32_bf16 v[78:81], v[156:159], v[220:223], v[78:81]
	v_mfma_f32_16x16x32_bf16 v[74:77], v[168:171], v[220:223], v[74:77]
	v_mfma_f32_16x16x32_bf16 v[126:129], v[164:167], v[200:203], v[126:129]
	v_mfma_f32_16x16x32_bf16 v[122:125], v[172:175], v[200:203], v[122:125]
	v_mfma_f32_16x16x32_bf16 v[110:113], v[164:167], v[208:211], v[110:113]
	v_mfma_f32_16x16x32_bf16 v[106:109], v[172:175], v[208:211], v[106:109]
	v_mfma_f32_16x16x32_bf16 v[94:97], v[164:167], v[216:219], v[94:97]
	v_mfma_f32_16x16x32_bf16 v[90:93], v[172:175], v[216:219], v[90:93]
	v_mfma_f32_16x16x32_bf16 v[78:81], v[164:167], v[224:227], v[78:81]
	v_mfma_f32_16x16x32_bf16 v[74:77], v[172:175], v[224:227], v[74:77]
	v_mfma_f32_16x16x32_bf16 v[118:121], v[176:179], v[192:195], v[118:121]
	v_mfma_f32_16x16x32_bf16 v[114:117], v[184:187], v[192:195], v[114:117]
	v_mfma_f32_16x16x32_bf16 v[102:105], v[176:179], v[204:207], v[102:105]
	v_mfma_f32_16x16x32_bf16 v[98:101], v[184:187], v[204:207], v[98:101]
	v_mfma_f32_16x16x32_bf16 v[86:89], v[176:179], v[212:215], v[86:89]
	v_mfma_f32_16x16x32_bf16 v[82:85], v[184:187], v[212:215], v[82:85]
	v_mfma_f32_16x16x32_bf16 v[70:73], v[176:179], v[220:223], v[70:73]
	v_mfma_f32_16x16x32_bf16 v[66:69], v[184:187], v[220:223], v[66:69]
	v_mfma_f32_16x16x32_bf16 v[118:121], v[180:183], v[200:203], v[118:121]
	v_mfma_f32_16x16x32_bf16 v[114:117], v[188:191], v[200:203], v[114:117]
	v_mfma_f32_16x16x32_bf16 v[102:105], v[180:183], v[208:211], v[102:105]
	v_mfma_f32_16x16x32_bf16 v[98:101], v[188:191], v[208:211], v[98:101]
	v_mfma_f32_16x16x32_bf16 v[86:89], v[180:183], v[216:219], v[86:89]
	v_mfma_f32_16x16x32_bf16 v[82:85], v[188:191], v[216:219], v[82:85]
	v_mfma_f32_16x16x32_bf16 v[70:73], v[180:183], v[224:227], v[70:73]
	v_mfma_f32_16x16x32_bf16 v[66:69], v[188:191], v[224:227], v[66:69]
	s_setprio 0
	s_barrier
; #define PG8_STAGE(bufoff, gbase, voff) do { _Pragma("unroll") for (int _i = 0; _i < 2; ++_i) \
;         __builtin_amdgcn_global_load_lds((const unsigned*)((const char*)(gbase) + (voff)[_i]), (PG8_LAS unsigned*)(lds + (bufoff) + ldsw + _i * 8192), 16, 0, 0); } while (0)
; #define PG8_LDA(dst, b, h) do { _Pragma("unroll") for (int m = 0; m < 4; ++m) _Pragma("unroll") for (int k = 0; k < 2; ++k) dst[m][k] = *(const PG8_LAS bf16x8*)(lds + PG8_SA(b, h) + aoff + m * 2048 + k * 1024); } while (0)
; #define PG8_MMA(ai, bj, At, Bt) do { __builtin_amdgcn_s_setprio(1); _Pragma("unroll") for (int m = 0; m < 4; ++m) _Pragma("unroll") for (int n = 0; n < 2; ++n) _Pragma("unroll") for (int k = 0; k < 2; ++k) \
;         acc[ai][bj][m][n] = __builtin_amdgcn_mfma_f32_16x16x32_bf16(Bt[n][k], At[m][k], acc[ai][bj][m][n], 0, 0, 0); __builtin_amdgcn_s_setprio(0); } while (0)
; #define PG8_WAIT_V(n) asm volatile("s_waitcnt vmcnt(" #n ")" ::: "memory")
; #define PG8_WAIT_L(n) asm volatile("s_waitcnt lgkmcnt(" #n ")" ::: "memory")
; #define PG8_BAR __builtin_amdgcn_s_barrier()
; #define PG8_SCHED __builtin_amdgcn_sched_barrier(0)
; template <class Epi, class Sched, bool ALIGN_EPI = false, bool SP2 = false, bool MID = false>
; __device__ __forceinline__ void gemm_phase(PG8_LAS unsigned char* lds, const Gemm g, const Sched& S, const Epi& E) {
;     ...
;         for (int t = 0; t < nt; t += 2) {
;             const bool last = (t == nt - 2);
;     ...
;             PG8_LDA(At, 1, 1); PG8_STAGE(PG8_SB(1, 0), b3, voffB); PG8_STAGE(PG8_SB(1, 1), b3 + hstep, voffB); PG8_STAGE(PG8_SA(1, 0), a3, voffA);
;             PG8_WAIT_V(8); PG8_WAIT_L(0); PG8_BAR; PG8_MMA(1, 0, At, B0); PG8_MMA(1, 1, At, B1); PG8_BAR; PG8_SCHED;
	s_add_i32 s36, s72, s41
	v_lshl_add_u64 v[196:197], v[196:197], 0, s[16:17]
	s_mov_b32 m0, s36
	ds_read_b128 v[192:195], v163 offset:49152
	ds_read_b128 v[200:203], v163 offset:50176
	ds_read_b128 v[204:207], v163 offset:51200
	ds_read_b128 v[208:211], v163 offset:52224
	ds_read_b128 v[212:215], v163 offset:53248
	ds_read_b128 v[216:219], v163 offset:54272
	ds_read_b128 v[220:223], v163 offset:55296
	ds_read_b128 v[224:227], v163 offset:56320
	global_load_lds_dwordx4 v[196:197], off
	s_add_i32 m0, s36, 0x2000
	s_add_u32 s26, s26, 0x90080
	v_lshl_add_u64 v[196:197], v[228:229], 0, s[16:17]
	s_addc_u32 s27, s27, 0
	s_add_i32 s36, s73, s41
	global_load_lds_dwordx4 v[196:197], off
	v_lshl_add_u64 v[196:197], s[26:27], 0, v[136:137]
	s_mov_b32 m0, s36
	s_nop 0
	global_load_lds_dwordx4 v[196:197], off
	v_lshl_add_u64 v[196:197], s[26:27], 0, v[140:141]
	s_add_i32 m0, s36, 0x2000
	s_nop 0
	global_load_lds_dwordx4 v[196:197], off
	v_lshl_add_u64 v[196:197], v[230:231], 0, s[16:17]
	s_mov_b32 m0, s48
	s_nop 0
	global_load_lds_dwordx4 v[196:197], off
	v_lshl_add_u64 v[196:197], v[232:233], 0, s[16:17]
	s_mov_b32 m0, s49
	s_nop 0
	global_load_lds_dwordx4 v[196:197], off
	s_waitcnt vmcnt(8)
	s_waitcnt lgkmcnt(0)
	s_barrier
	s_setprio 1
	s_waitcnt lgkmcnt(0)
	v_mfma_f32_16x16x32_bf16 v[62:65], v[156:159], v[192:195], v[62:65]
	v_mfma_f32_16x16x32_bf16 v[58:61], v[168:171], v[192:195], v[58:61]
	v_mfma_f32_16x16x32_bf16 v[46:49], v[156:159], v[204:207], v[46:49]
	v_mfma_f32_16x16x32_bf16 v[42:45], v[168:171], v[204:207], v[42:45]
	v_mfma_f32_16x16x32_bf16 v[30:33], v[156:159], v[212:215], v[30:33]
	v_mfma_f32_16x16x32_bf16 v[26:29], v[168:171], v[212:215], v[26:29]
	v_mfma_f32_16x16x32_bf16 v[14:17], v[156:159], v[220:223], v[14:17]
	v_mfma_f32_16x16x32_bf16 v[10:13], v[168:171], v[220:223], v[10:13]
	v_mfma_f32_16x16x32_bf16 v[62:65], v[164:167], v[200:203], v[62:65]
	v_mfma_f32_16x16x32_bf16 v[58:61], v[172:175], v[200:203], v[58:61]
	v_mfma_f32_16x16x32_bf16 v[46:49], v[164:167], v[208:211], v[46:49]
	v_mfma_f32_16x16x32_bf16 v[42:45], v[172:175], v[208:211], v[42:45]
	v_mfma_f32_16x16x32_bf16 v[30:33], v[164:167], v[216:219], v[30:33]
	v_mfma_f32_16x16x32_bf16 v[26:29], v[172:175], v[216:219], v[26:29]
	v_mfma_f32_16x16x32_bf16 v[14:17], v[164:167], v[224:227], v[14:17]
	v_mfma_f32_16x16x32_bf16 v[10:13], v[172:175], v[224:227], v[10:13]
	v_mfma_f32_16x16x32_bf16 v[54:57], v[176:179], v[192:195], v[54:57]
	v_mfma_f32_16x16x32_bf16 v[50:53], v[184:187], v[192:195], v[50:53]
	v_mfma_f32_16x16x32_bf16 v[38:41], v[176:179], v[204:207], v[38:41]
	v_mfma_f32_16x16x32_bf16 v[34:37], v[184:187], v[204:207], v[34:37]
	v_mfma_f32_16x16x32_bf16 v[22:25], v[176:179], v[212:215], v[22:25]
	v_mfma_f32_16x16x32_bf16 v[18:21], v[184:187], v[212:215], v[18:21]
	v_mfma_f32_16x16x32_bf16 v[6:9], v[176:179], v[220:223], v[6:9]
	v_mfma_f32_16x16x32_bf16 v[2:5], v[184:187], v[220:223], v[2:5]
	v_mfma_f32_16x16x32_bf16 v[54:57], v[180:183], v[200:203], v[54:57]
	v_mfma_f32_16x16x32_bf16 v[50:53], v[188:191], v[200:203], v[50:53]
	v_mfma_f32_16x16x32_bf16 v[38:41], v[180:183], v[208:211], v[38:41]
	v_mfma_f32_16x16x32_bf16 v[34:37], v[188:191], v[208:211], v[34:37]
	v_mfma_f32_16x16x32_bf16 v[22:25], v[180:183], v[216:219], v[22:25]
	v_mfma_f32_16x16x32_bf16 v[18:21], v[188:191], v[216:219], v[18:21]
	v_mfma_f32_16x16x32_bf16 v[6:9], v[180:183], v[224:227], v[6:9]
	v_mfma_f32_16x16x32_bf16 v[2:5], v[188:191], v[224:227], v[2:5]
	s_setprio 0
	s_barrier
	s_add_i32 s71, s71, 2
	s_add_u32 s24, s24, 0x100
	s_addc_u32 s25, s25, 0
	s_cmp_gt_u32 s71, 33
	s_cbranch_scc1 .LBB0_1940
